# peel first K-tile of every non-first GEMM unit: no accumulator zeroing (first MFMA per accumulator takes SrcC=0), wave-group stagger barrier moved after unit set-up
# speedup vs baseline: 1.0071x; 1.0071x over previous
;     __host__ __device__ __forceinline__ bool next(int i, Unit& u) const { const int vv = vid + (i / 5) * G; if (vv >= 256) return false; u.pm = vv >> 2; u.pn = (vv & 3) + 4 * (i % 5); return true; }
;     __host__ __device__ __forceinline__ bool next(int i, pg8::Unit& u) const { const long Lx = (long)i * G + c; if (Lx >= 128) return false; const int Lq = (int)Lx; u.pm = 8 * (Lq >> 5) + (Lq & 7); u.pn = (Lq >> 3) & 3; return true; }
;     __device__ __forceinline__ size_t b_off(const pg8::Unit& u) const { return (size_t)(u.pm >> 3) * 4 * 131072; }
;     ...
;     for (;;) {
;         const bool has_next = S.next(ui + 1, nxt);
;         const char* nA = has_next ? (const char*)g.A + (size_t)nxt.pm * tstepA + (size_t)nxt.pn * APN + kofA : cA; const char* nB = has_next ? (const char*)g.Bt + (size_t)nxt.pn * tstepB + S.b_off(nxt) + kofB : cB;
.LBB0_324:
	s_andn2_b64 vcc, exec, s[6:7]
	s_mov_b32 s41, s30
	s_mov_b32 s8, s28
	s_mov_b64 s[86:87], s[46:47]
	s_mov_b64 s[6:7], s[34:35]
	s_mov_b32 s9, s40
	s_cbranch_vccz .LBB0_630
	s_branch .Lin_setup2

; #define PG8_STAGE(bufoff, gbase, voff) do { _Pragma("unroll") for (int _i = 0; _i < 2; ++_i) \
;         __builtin_amdgcn_global_load_lds((const unsigned*)((const char*)(gbase) + (voff)[_i]), (PG8_LAS unsigned*)(lds + (bufoff) + ldsw + _i * 8192), 16, 0, 0); } while (0)
; #define PG8_LDA(dst, b, h) do { _Pragma("unroll") for (int m = 0; m < 4; ++m) _Pragma("unroll") for (int k = 0; k < 2; ++k) dst[m][k] = *(const PG8_LAS bf16x8*)(lds + PG8_SA(b, h) + aoff + m * 2048 + k * 1024); } while (0)
; #define PG8_LDB(dst, b, h) do { _Pragma("unroll") for (int n = 0; n < 2; ++n) _Pragma("unroll") for (int k = 0; k < 2; ++k) dst[n][k] = *(const PG8_LAS bf16x8*)(lds + PG8_SB(b, h) + boff + n * 2048 + k * 1024); } while (0)
; #define PG8_MMA(ai, bj, At, Bt) do { __builtin_amdgcn_s_setprio(1); _Pragma("unroll") for (int m = 0; m < 4; ++m) _Pragma("unroll") for (int n = 0; n < 2; ++n) _Pragma("unroll") for (int k = 0; k < 2; ++k) \
;         acc[ai][bj][m][n] = __builtin_amdgcn_mfma_f32_16x16x32_bf16(Bt[n][k], At[m][k], acc[ai][bj][m][n], 0, 0, 0); __builtin_amdgcn_s_setprio(0); } while (0)
; #define PG8_WAIT_V(n) asm volatile("s_waitcnt vmcnt(" #n ")" ::: "memory")
;     ...
;         const char* nA = has_next ? (const char*)g.A + (size_t)nxt.pm * tstepA + (size_t)nxt.pn * APN + kofA : cA; const char* nB = has_next ? (const char*)g.Bt + (size_t)nxt.pn * tstepB + S.b_off(nxt) + kofB : cB;
;         for (int t = 0; t < nt; t += 2) {
;             const bool last = (t == nt - 2);
;             const char* a1 = cA + (ptrdiff_t)(t + 1) * kstepA;
;             const char* a2 = last ? nA : cA + (ptrdiff_t)(t + 2) * kstepA; const char* b2 = last ? nB : cB + (ptrdiff_t)(t + 2) * kstep;
;             const char* a3 = a2 + kstepA; const char* b3 = b2 + kstep;
;             if (last && has_next) S.a_ready(nxt);
;             if constexpr (SP2) {
;             PG8_LDB(B0, 0, 0); PG8_LDB(B1, 0, 1); PG8_SCHED; PG8_LDA(At, 0, 0); PG8_STAGE(PG8_SA(1, 1), a1 + hstepA, voffA);
;             PG8_WAIT_V(8); PG8_WAIT_L(0); PG8_BAR; PG8_MMA(0, 0, At, B0); PG8_MMA(0, 1, At, B1); PG8_BAR; PG8_SCHED;
;             PG8_LDA(At, 0, 1); PG8_STAGE(PG8_SB(0, 0), b2, voffB); PG8_STAGE(PG8_SB(0, 1), b2 + hstepB, voffB); PG8_STAGE(PG8_SA(0, 0), a2, voffA);
;             PG8_WAIT_V(8); PG8_WAIT_L(0); PG8_BAR; PG8_MMA(1, 0, At, B0); PG8_MMA(1, 1, At, B1); PG8_BAR; PG8_SCHED;
.Lin_s_327:
	s_ashr_i32 s29, s28, 31
	s_lshl_b64 s[34:35], s[28:29], 20
	s_add_u32 s34, s61, s34
	s_addc_u32 s35, s63, s35
	s_and_b64 s[46:47], s[36:37], exec
	s_cselect_b32 s29, s35, s7
	s_cselect_b32 s54, s34, s6
	s_ashr_i32 s31, s30, 31
	s_lshl_b64 s[46:47], s[30:31], 20
	s_add_u32 s46, s48, s46
	s_addc_u32 s47, s49, s47
	s_and_b64 s[56:57], s[36:37], exec
	s_cselect_b32 s31, s47, s87
	s_cselect_b32 s55, s46, s86
	s_add_u32 s6, s6, 0xc000
	s_addc_u32 s7, s7, 0
	s_add_u32 s56, s86, 0x10000
	s_addc_u32 s57, s87, 0
	s_mov_b32 vcc_lo, -2
	s_cmp_eq_u64 s[16:17], 0
	s_cbranch_scc1 .Lin_nostg
	s_barrier
.Lin_nostg:
	s_add_u32 s65, s6, 0x4000
	s_addc_u32 s66, s7, 0
	s_cmp_eq_u32 vcc_lo, 28
	s_cselect_b32 s90, s54, s65
	s_cselect_b32 s91, s29, s66
	s_cselect_b32 s88, s55, s56
	s_cselect_b32 s89, s31, s57
	s_add_u32 s86, s90, 0x8000
	s_addc_u32 s87, s91, 0
	s_add_i32 s65, 0, 0x10000
	s_add_i32 s66, 0, 0x14000
	v_add_u32_e32 v22, s65, v182
	v_add_u32_e32 v54, s66, v182
	ds_read_b128 v[10:13], v22
	ds_read_b128 v[14:17], v22 offset:1024
	ds_read_b128 v[18:21], v22 offset:2048
	ds_read_b128 v[22:25], v22 offset:3072
	ds_read_b128 v[26:29], v54
	ds_read_b128 v[38:41], v54 offset:1024
	ds_read_b128 v[50:53], v54 offset:2048
	ds_read_b128 v[54:57], v54 offset:3072
	s_add_i32 m0, s51, 0xc000
	ds_read_b128 v[172:175], v183
	ds_read_b128 v[176:179], v183 offset:1024
	ds_read_b128 v[184:187], v183 offset:2048
	ds_read_b128 v[188:191], v183 offset:3072
	ds_read_b128 v[192:195], v183 offset:4096
	ds_read_b128 v[196:199], v183 offset:5120
	ds_read_b128 v[200:203], v183 offset:6144
	ds_read_b128 v[204:207], v183 offset:7168
	global_load_lds_dwordx4 v168, s[6:7]
	s_add_i32 m0, s51, 0xe000
	s_nop 0
	global_load_lds_dwordx4 v170, s[6:7]
	s_waitcnt vmcnt(8)
	s_waitcnt lgkmcnt(0)
	s_barrier
	s_setprio 1
	s_waitcnt lgkmcnt(0)
	v_mfma_f32_16x16x32_bf16 v[158:161], v[10:13], v[172:175], 0
	v_mfma_f32_16x16x32_bf16 v[158:161], v[14:17], v[176:179], v[158:161]
	v_mfma_f32_16x16x32_bf16 v[154:157], v[22:25], v[176:179], 0
	v_mfma_f32_16x16x32_bf16 v[154:157], v[18:21], v[172:175], v[154:157]
	v_mfma_f32_16x16x32_bf16 v[138:141], v[18:21], v[184:187], 0
	v_mfma_f32_16x16x32_bf16 v[138:141], v[22:25], v[188:191], v[138:141]
	v_mfma_f32_16x16x32_bf16 v[142:145], v[14:17], v[188:191], 0
	v_mfma_f32_16x16x32_bf16 v[142:145], v[10:13], v[184:187], v[142:145]
	v_mfma_f32_16x16x32_bf16 v[126:129], v[10:13], v[192:195], 0
	v_mfma_f32_16x16x32_bf16 v[126:129], v[14:17], v[196:199], v[126:129]
	v_mfma_f32_16x16x32_bf16 v[122:125], v[22:25], v[196:199], 0
	v_mfma_f32_16x16x32_bf16 v[122:125], v[18:21], v[192:195], v[122:125]
	v_mfma_f32_16x16x32_bf16 v[106:109], v[18:21], v[200:203], 0
	v_mfma_f32_16x16x32_bf16 v[106:109], v[22:25], v[204:207], v[106:109]
	v_mfma_f32_16x16x32_bf16 v[110:113], v[14:17], v[204:207], 0
	v_mfma_f32_16x16x32_bf16 v[110:113], v[10:13], v[200:203], v[110:113]
	s_setprio 0
	s_setprio 1
	v_mfma_f32_16x16x32_bf16 v[150:153], v[26:29], v[172:175], 0
	v_mfma_f32_16x16x32_bf16 v[150:153], v[38:41], v[176:179], v[150:153]
	v_mfma_f32_16x16x32_bf16 v[146:149], v[54:57], v[176:179], 0
	v_mfma_f32_16x16x32_bf16 v[146:149], v[50:53], v[172:175], v[146:149]
	v_mfma_f32_16x16x32_bf16 v[130:133], v[50:53], v[184:187], 0
	v_mfma_f32_16x16x32_bf16 v[130:133], v[54:57], v[188:191], v[130:133]
	v_mfma_f32_16x16x32_bf16 v[134:137], v[38:41], v[188:191], 0
	v_mfma_f32_16x16x32_bf16 v[134:137], v[26:29], v[184:187], v[134:137]
	v_mfma_f32_16x16x32_bf16 v[118:121], v[26:29], v[192:195], 0
	v_mfma_f32_16x16x32_bf16 v[118:121], v[38:41], v[196:199], v[118:121]
	v_mfma_f32_16x16x32_bf16 v[114:117], v[54:57], v[196:199], 0
	v_mfma_f32_16x16x32_bf16 v[114:117], v[50:53], v[192:195], v[114:117]
	v_mfma_f32_16x16x32_bf16 v[98:101], v[50:53], v[200:203], 0
	v_mfma_f32_16x16x32_bf16 v[98:101], v[54:57], v[204:207], v[98:101]
	v_mfma_f32_16x16x32_bf16 v[102:105], v[38:41], v[204:207], 0
	v_mfma_f32_16x16x32_bf16 v[102:105], v[26:29], v[200:203], v[102:105]
	s_setprio 0
	s_barrier
	s_add_i32 s65, s65, s2
	s_mov_b32 m0, s65
	ds_read_b128 v[172:175], v183 offset:16384
	ds_read_b128 v[176:179], v183 offset:17408
	ds_read_b128 v[184:187], v183 offset:18432
	ds_read_b128 v[188:191], v183 offset:19456
	ds_read_b128 v[192:195], v183 offset:20480
	ds_read_b128 v[196:199], v183 offset:21504
	ds_read_b128 v[200:203], v183 offset:22528
	ds_read_b128 v[204:207], v183 offset:23552
	global_load_lds_dwordx4 v0, s[88:89]
	s_add_i32 m0, s65, 0x2000
	s_add_u32 s96, s88, 0x4000
	s_addc_u32 s97, s89, 0
	s_add_i32 s65, s66, s2
	global_load_lds_dwordx4 v162, s[88:89]
	s_mov_b32 m0, s65
	s_nop 0
	global_load_lds_dwordx4 v0, s[96:97]
	s_add_i32 m0, s65, 0x2000
	s_nop 0
	global_load_lds_dwordx4 v162, s[96:97]
	s_mov_b32 m0, s51
	s_nop 0
	global_load_lds_dwordx4 v166, s[90:91]
	s_mov_b32 m0, s92
	s_nop 0
	global_load_lds_dwordx4 v164, s[90:91]
	s_waitcnt vmcnt(8)
	s_waitcnt lgkmcnt(0)
	s_barrier
	s_setprio 1
	s_waitcnt lgkmcnt(0)
	v_mfma_f32_16x16x32_bf16 v[94:97], v[10:13], v[172:175], 0
	v_mfma_f32_16x16x32_bf16 v[94:97], v[14:17], v[176:179], v[94:97]
	v_mfma_f32_16x16x32_bf16 v[90:93], v[18:21], v[172:175], 0
	v_mfma_f32_16x16x32_bf16 v[90:93], v[22:25], v[176:179], v[90:93]
	v_mfma_f32_16x16x32_bf16 v[78:81], v[10:13], v[184:187], 0
	v_mfma_f32_16x16x32_bf16 v[78:81], v[14:17], v[188:191], v[78:81]
	v_mfma_f32_16x16x32_bf16 v[74:77], v[18:21], v[184:187], 0
	v_mfma_f32_16x16x32_bf16 v[74:77], v[22:25], v[188:191], v[74:77]
	v_mfma_f32_16x16x32_bf16 v[62:65], v[10:13], v[192:195], 0
	v_mfma_f32_16x16x32_bf16 v[62:65], v[14:17], v[196:199], v[62:65]
	v_mfma_f32_16x16x32_bf16 v[58:61], v[18:21], v[192:195], 0
	v_mfma_f32_16x16x32_bf16 v[58:61], v[22:25], v[196:199], v[58:61]
	v_mfma_f32_16x16x32_bf16 v[10:13], v[10:13], v[200:203], 0
	v_mfma_f32_16x16x32_bf16 v[10:13], v[14:17], v[204:207], v[10:13]
	v_mfma_f32_16x16x32_bf16 v[14:17], v[18:21], v[200:203], 0
	v_mfma_f32_16x16x32_bf16 v[14:17], v[22:25], v[204:207], v[14:17]
	s_setprio 0
	s_setprio 1
	v_mfma_f32_16x16x32_bf16 v[30:33], v[26:29], v[184:187], 0
	v_mfma_f32_16x16x32_bf16 v[70:73], v[38:41], v[188:191], v[30:33]
	v_mfma_f32_16x16x32_bf16 v[30:33], v[50:53], v[184:187], 0
	v_mfma_f32_16x16x32_bf16 v[66:69], v[54:57], v[188:191], v[30:33]
	v_mfma_f32_16x16x32_bf16 v[30:33], v[26:29], v[192:195], 0
	v_mfma_f32_16x16x32_bf16 v[46:49], v[38:41], v[196:199], v[30:33]
	v_mfma_f32_16x16x32_bf16 v[30:33], v[50:53], v[192:195], 0
	v_mfma_f32_16x16x32_bf16 v[42:45], v[54:57], v[196:199], v[30:33]
	v_mfma_f32_16x16x32_bf16 v[6:9], v[26:29], v[200:203], 0
	v_mfma_f32_16x16x32_bf16 v[6:9], v[38:41], v[204:207], v[6:9]
	v_mfma_f32_16x16x32_bf16 v[2:5], v[50:53], v[200:203], 0
	v_mfma_f32_16x16x32_bf16 v[2:5], v[54:57], v[204:207], v[2:5]
	v_mfma_f32_16x16x32_bf16 v[18:21], v[26:29], v[172:175], 0
	v_mfma_f32_16x16x32_bf16 v[18:21], v[38:41], v[176:179], v[18:21]
	v_mfma_f32_16x16x32_bf16 v[22:25], v[50:53], v[172:175], 0
	v_mfma_f32_16x16x32_bf16 v[22:25], v[54:57], v[176:179], v[22:25]
	s_setprio 0
	s_barrier
	s_branch .Lin_mid

; #define PG8_STAGE(bufoff, gbase, voff) do { _Pragma("unroll") for (int _i = 0; _i < 2; ++_i) \
;         __builtin_amdgcn_global_load_lds((const unsigned*)((const char*)(gbase) + (voff)[_i]), (PG8_LAS unsigned*)(lds + (bufoff) + ldsw + _i * 8192), 16, 0, 0); } while (0)
; #define PG8_LDA(dst, b, h) do { _Pragma("unroll") for (int m = 0; m < 4; ++m) _Pragma("unroll") for (int k = 0; k < 2; ++k) dst[m][k] = *(const PG8_LAS bf16x8*)(lds + PG8_SA(b, h) + aoff + m * 2048 + k * 1024); } while (0)
; #define PG8_LDB(dst, b, h) do { _Pragma("unroll") for (int n = 0; n < 2; ++n) _Pragma("unroll") for (int k = 0; k < 2; ++k) dst[n][k] = *(const PG8_LAS bf16x8*)(lds + PG8_SB(b, h) + boff + n * 2048 + k * 1024); } while (0)
; #define PG8_MMA(ai, bj, At, Bt) do { __builtin_amdgcn_s_setprio(1); _Pragma("unroll") for (int m = 0; m < 4; ++m) _Pragma("unroll") for (int n = 0; n < 2; ++n) _Pragma("unroll") for (int k = 0; k < 2; ++k) \
;         acc[ai][bj][m][n] = __builtin_amdgcn_mfma_f32_16x16x32_bf16(Bt[n][k], At[m][k], acc[ai][bj][m][n], 0, 0, 0); __builtin_amdgcn_s_setprio(0); } while (0)
; #define PG8_WAIT_V(n) asm volatile("s_waitcnt vmcnt(" #n ")" ::: "memory")
; #define PG8_WAIT_L(n) asm volatile("s_waitcnt lgkmcnt(" #n ")" ::: "memory")
; #define PG8_BAR __builtin_amdgcn_s_barrier()
; #define PG8_SCHED __builtin_amdgcn_sched_barrier(0)
;     ...
;             PG8_LDB(B0, 1, 0); PG8_LDB(B1, 1, 1); PG8_SCHED; PG8_LDA(At, 1, 0); PG8_STAGE(PG8_SA(0, 1), a2 + hstepA, voffA);
;             PG8_WAIT_V(8); PG8_WAIT_L(0); PG8_BAR; PG8_MMA(0, 0, At, B0); PG8_MMA(0, 1, At, B1); PG8_BAR; PG8_SCHED;
;             PG8_LDA(At, 1, 1); PG8_STAGE(PG8_SB(1, 0), b3, voffB); PG8_STAGE(PG8_SB(1, 1), b3 + hstepB, voffB); PG8_STAGE(PG8_SA(1, 0), a3, voffA);
;             PG8_WAIT_V(8); PG8_WAIT_L(0); PG8_BAR; PG8_MMA(1, 0, At, B0); PG8_MMA(1, 1, At, B1); PG8_BAR; PG8_SCHED;
.Lin_mid:
	s_add_i32 s65, 0, 0x18000
	v_add_u32_e32 v34, s65, v182
	s_add_i32 s66, 0, 0x1c000
	ds_read_b128 v[26:29], v34
	ds_read_b128 v[30:33], v34 offset:1024
	ds_read_b128 v[38:41], v34 offset:2048
	ds_read_b128 v[50:53], v34 offset:3072
	v_add_u32_e32 v34, s66, v182
	ds_read_b128 v[54:57], v34
	ds_read_b128 v[172:175], v34 offset:1024
	ds_read_b128 v[176:179], v34 offset:2048
	ds_read_b128 v[184:187], v34 offset:3072
	s_add_u32 s90, s90, 0x4000
	s_addc_u32 s91, s91, 0
	s_mov_b32 m0, s14
	ds_read_b128 v[34:37], v183 offset:32768
	ds_read_b128 v[82:85], v183 offset:33792
	ds_read_b128 v[86:89], v183 offset:34816
	ds_read_b128 v[188:191], v183 offset:35840
	ds_read_b128 v[192:195], v183 offset:36864
	ds_read_b128 v[196:199], v183 offset:37888
	ds_read_b128 v[200:203], v183 offset:38912
	ds_read_b128 v[204:207], v183 offset:39936
	global_load_lds_dwordx4 v166, s[90:91]
	v_lshl_add_u64 v[208:209], s[90:91], 0, v[164:165]
	s_mov_b32 m0, s15
	s_nop 0
	global_load_lds_dwordx4 v[208:209], off
	s_waitcnt vmcnt(8)
	s_waitcnt lgkmcnt(0)
	s_barrier
	s_setprio 1
	s_waitcnt lgkmcnt(0)
	v_mfma_f32_16x16x32_bf16 v[158:161], v[26:29], v[34:37], v[158:161]
	v_mfma_f32_16x16x32_bf16 v[158:161], v[30:33], v[82:85], v[158:161]
	v_mfma_f32_16x16x32_bf16 v[154:157], v[50:53], v[82:85], v[154:157]
	v_mfma_f32_16x16x32_bf16 v[154:157], v[38:41], v[34:37], v[154:157]
	v_mfma_f32_16x16x32_bf16 v[138:141], v[38:41], v[86:89], v[138:141]
	v_mfma_f32_16x16x32_bf16 v[138:141], v[50:53], v[188:191], v[138:141]
	v_mfma_f32_16x16x32_bf16 v[142:145], v[30:33], v[188:191], v[142:145]
	v_mfma_f32_16x16x32_bf16 v[142:145], v[26:29], v[86:89], v[142:145]
	v_mfma_f32_16x16x32_bf16 v[126:129], v[26:29], v[192:195], v[126:129]
	v_mfma_f32_16x16x32_bf16 v[126:129], v[30:33], v[196:199], v[126:129]
	v_mfma_f32_16x16x32_bf16 v[122:125], v[50:53], v[196:199], v[122:125]
	v_mfma_f32_16x16x32_bf16 v[122:125], v[38:41], v[192:195], v[122:125]
	v_mfma_f32_16x16x32_bf16 v[106:109], v[38:41], v[200:203], v[106:109]
	v_mfma_f32_16x16x32_bf16 v[106:109], v[50:53], v[204:207], v[106:109]
	v_mfma_f32_16x16x32_bf16 v[110:113], v[30:33], v[204:207], v[110:113]
	v_mfma_f32_16x16x32_bf16 v[110:113], v[26:29], v[200:203], v[110:113]
	s_setprio 0
	s_setprio 1
	v_mfma_f32_16x16x32_bf16 v[150:153], v[54:57], v[34:37], v[150:153]
	v_mfma_f32_16x16x32_bf16 v[150:153], v[172:175], v[82:85], v[150:153]
	v_mfma_f32_16x16x32_bf16 v[34:37], v[176:179], v[34:37], v[146:149]
	v_mfma_f32_16x16x32_bf16 v[146:149], v[184:187], v[82:85], v[34:37]
	v_mfma_f32_16x16x32_bf16 v[34:37], v[54:57], v[86:89], v[134:137]
	v_mfma_f32_16x16x32_bf16 v[134:137], v[172:175], v[188:191], v[34:37]
	v_mfma_f32_16x16x32_bf16 v[34:37], v[176:179], v[86:89], v[130:133]
	v_mfma_f32_16x16x32_bf16 v[130:133], v[184:187], v[188:191], v[34:37]
	v_mfma_f32_16x16x32_bf16 v[34:37], v[54:57], v[192:195], v[118:121]
	v_mfma_f32_16x16x32_bf16 v[118:121], v[172:175], v[196:199], v[34:37]
	v_mfma_f32_16x16x32_bf16 v[34:37], v[176:179], v[192:195], v[114:117]
	v_mfma_f32_16x16x32_bf16 v[114:117], v[184:187], v[196:199], v[34:37]
	v_mfma_f32_16x16x32_bf16 v[34:37], v[54:57], v[200:203], v[102:105]
	v_mfma_f32_16x16x32_bf16 v[102:105], v[172:175], v[204:207], v[34:37]
	v_mfma_f32_16x16x32_bf16 v[34:37], v[176:179], v[200:203], v[98:101]
	v_mfma_f32_16x16x32_bf16 v[98:101], v[184:187], v[204:207], v[34:37]
	s_setprio 0
	s_barrier
	s_add_u32 s90, s88, 0x8000
	s_addc_u32 s91, s89, 0
	s_add_i32 s65, s65, s2
	s_nop 0
	s_mov_b32 m0, s65
	ds_read_b128 v[82:85], v183 offset:49152
	ds_read_b128 v[188:191], v183 offset:50176
	ds_read_b128 v[192:195], v183 offset:51200
	ds_read_b128 v[196:199], v183 offset:52224
	ds_read_b128 v[200:203], v183 offset:53248
	ds_read_b128 v[204:207], v183 offset:54272
	ds_read_b128 v[208:211], v183 offset:55296
	ds_read_b128 v[216:219], v183 offset:56320
	global_load_lds_dwordx4 v0, s[90:91]
	s_add_i32 m0, s65, 0x2000
	s_add_u32 s88, s88, 0xc000
	s_addc_u32 s89, s89, 0
	s_add_i32 s65, s66, s2
	global_load_lds_dwordx4 v162, s[90:91]
	s_mov_b32 m0, s65
	s_nop 0
	global_load_lds_dwordx4 v0, s[88:89]
	s_add_i32 m0, s65, 0x2000
	s_nop 0
	global_load_lds_dwordx4 v162, s[88:89]
	s_mov_b32 m0, s71
	s_nop 0
	global_load_lds_dwordx4 v166, s[86:87]
	v_lshl_add_u64 v[34:35], s[86:87], 0, v[164:165]
	s_mov_b32 m0, s80
	s_nop 0
	global_load_lds_dwordx4 v[34:35], off
	s_waitcnt vmcnt(8)
	s_waitcnt lgkmcnt(0)
	s_barrier
	s_setprio 1
	s_waitcnt lgkmcnt(0)
	v_mfma_f32_16x16x32_bf16 v[34:37], v[26:29], v[82:85], v[94:97]
	v_mfma_f32_16x16x32_bf16 v[94:97], v[30:33], v[188:191], v[34:37]
	v_mfma_f32_16x16x32_bf16 v[34:37], v[38:41], v[82:85], v[90:93]
	v_mfma_f32_16x16x32_bf16 v[90:93], v[50:53], v[188:191], v[34:37]
	v_mfma_f32_16x16x32_bf16 v[34:37], v[26:29], v[192:195], v[78:81]
	v_mfma_f32_16x16x32_bf16 v[78:81], v[30:33], v[196:199], v[34:37]
	v_mfma_f32_16x16x32_bf16 v[34:37], v[38:41], v[192:195], v[74:77]
	v_mfma_f32_16x16x32_bf16 v[74:77], v[50:53], v[196:199], v[34:37]
	v_mfma_f32_16x16x32_bf16 v[34:37], v[26:29], v[200:203], v[62:65]
	v_mfma_f32_16x16x32_bf16 v[62:65], v[30:33], v[204:207], v[34:37]
	v_mfma_f32_16x16x32_bf16 v[34:37], v[38:41], v[200:203], v[58:61]
	v_mfma_f32_16x16x32_bf16 v[58:61], v[50:53], v[204:207], v[34:37]
	v_mfma_f32_16x16x32_bf16 v[10:13], v[26:29], v[208:211], v[10:13]
	v_mfma_f32_16x16x32_bf16 v[34:37], v[30:33], v[216:219], v[10:13]
	v_mfma_f32_16x16x32_bf16 v[10:13], v[38:41], v[208:211], v[14:17]
	v_mfma_f32_16x16x32_bf16 v[30:33], v[50:53], v[216:219], v[10:13]
	s_setprio 0
	s_setprio 1
	v_mfma_f32_16x16x32_bf16 v[10:13], v[54:57], v[82:85], v[18:21]
	v_mfma_f32_16x16x32_bf16 v[86:89], v[172:175], v[188:191], v[10:13]
	v_mfma_f32_16x16x32_bf16 v[10:13], v[176:179], v[82:85], v[22:25]
	v_mfma_f32_16x16x32_bf16 v[82:85], v[184:187], v[188:191], v[10:13]
	v_mfma_f32_16x16x32_bf16 v[10:13], v[54:57], v[192:195], v[70:73]
	v_mfma_f32_16x16x32_bf16 v[70:73], v[172:175], v[196:199], v[10:13]
	v_mfma_f32_16x16x32_bf16 v[10:13], v[176:179], v[192:195], v[66:69]
	v_mfma_f32_16x16x32_bf16 v[66:69], v[184:187], v[196:199], v[10:13]
	v_mfma_f32_16x16x32_bf16 v[10:13], v[54:57], v[200:203], v[46:49]
	v_mfma_f32_16x16x32_bf16 v[46:49], v[172:175], v[204:207], v[10:13]
	v_mfma_f32_16x16x32_bf16 v[10:13], v[176:179], v[200:203], v[42:45]
	v_mfma_f32_16x16x32_bf16 v[42:45], v[184:187], v[204:207], v[10:13]
	v_mfma_f32_16x16x32_bf16 v[6:9], v[54:57], v[208:211], v[6:9]
	v_mfma_f32_16x16x32_bf16 v[6:9], v[172:175], v[216:219], v[6:9]
	v_mfma_f32_16x16x32_bf16 v[2:5], v[176:179], v[208:211], v[2:5]
	v_mfma_f32_16x16x32_bf16 v[2:5], v[184:187], v[216:219], v[2:5]
	s_setprio 0
	s_barrier
	s_add_i32 vcc_lo, vcc_lo, 2
	s_add_u32 s6, s6, 0x10000
	s_addc_u32 s7, s7, 0
	s_add_u32 s56, s56, 0x10000
	s_addc_u32 s57, s57, 0
	s_cmp_gt_u32 vcc_lo, 29
	s_cbranch_scc0 .LBB0_328
	s_and_b64 vcc, exec, s[26:27]
	s_cbranch_vccz .LBB0_331
	s_barrier

; __device__ __forceinline__ float logf_of(float p, float lb) { const float sig = __builtin_amdgcn_rcpf(1.f + __expf(-p)); const float f = lb + (1.f - lb) * sig; return fmaxf(__logf(f), -60.f); }
; #define PG8_BAR __builtin_amdgcn_s_barrier()
; __device__ __forceinline__ u32x4 pack8(const f32x4 a, const f32x4 b) { u32x4 w; w.x = cvt_pk_bf16(a.x, a.y); w.y = cvt_pk_bf16(a.z, a.w); w.z = cvt_pk_bf16(b.x, b.y); w.w = cvt_pk_bf16(b.z, b.w); return w; }
; __device__ __forceinline__ f32x4 silu4(const f32x4 p) { f32x4 r; r.x = siluf(p.x); r.y = siluf(p.y); r.z = siluf(p.z); r.w = siluf(p.w); return r; }
; __device__ __forceinline__ void store_wt(void* p, const u32x4 v) { asm volatile("global_store_dwordx4 %0, %1, off sc1\n\ts_nop 2" :: "v"(p), "v"(v) : "memory"); }
;     ...
;         if constexpr (ALIGN_EPI) { if (wr == 1) PG8_BAR; }
;     __device__ __forceinline__ void operator()(f32x4 (&acc)[2][2][4][2], const pg8::Unit& u, int ui, int wr, int wc, int fr, int fq) const {
;     ...
;                     f32x4 p0 = acc[ai][bj][m][0] * r + sw[bj][0], p1 = acc[ai][bj][m][1] * r + sw[bj][1];
;                     const size_t o = (size_t)row * DH + colt + bj * 128;
;                     if (grp == 0) { *(u32x4*)(Q + o) = pack8(silu4(p0) * QSCALE, silu4(p1) * QSCALE); }
;                     else if (grp == 1) { f32x4 l0, l1; l0.x = logf_of(p0.x, lb[bj][0].x); l0.y = logf_of(p0.y, lb[bj][0].y); l0.z = logf_of(p0.z, lb[bj][0].z); l0.w = logf_of(p0.w, lb[bj][0].w);
;                         l1.x = logf_of(p1.x, lb[bj][1].x); l1.y = logf_of(p1.y, lb[bj][1].y); l1.z = logf_of(p1.z, lb[bj][1].z); l1.w = logf_of(p1.w, lb[bj][1].w);
;                         const f32x8_t ff = {l0.x, l0.y, l0.z, l0.w, l1.x, l1.y, l1.z, l1.w}; *(f16x8_t*)(LF + o) = __builtin_convertvector(ff, f16x8_t); }
;                     else if (grp == 2) { *(u32x4*)(V + o) = pack8(p0, p1); }
;                     else if (grp == 3) { *(u32x4*)(SG + o) = pack8(silu4(p0), silu4(p1)); }
;                     else { store_wt(U + o, pack8(p0, p1)); }
.LBB0_483:
	v_mul_f32_e32 v12, 0xbfb8aa3b, v8
	v_mul_f32_e32 v13, 0xbfb8aa3b, v9
	v_exp_f32_e32 v12, v12
	v_exp_f32_e32 v13, v13
	v_mul_f32_e32 v14, 0xbfb8aa3b, v6
	v_mul_f32_e32 v15, 0xbfb8aa3b, v7
	v_add_f32_e32 v12, 1.0, v12
	v_add_f32_e32 v13, 1.0, v13
	v_rcp_f32_e32 v12, v12
	v_rcp_f32_e32 v13, v13
	v_exp_f32_e32 v14, v14
	v_exp_f32_e32 v15, v15
	v_mul_f32_e32 v10, 0xbfb8aa3b, v18
	v_mul_f32_e32 v11, 0xbfb8aa3b, v19
	v_pk_mul_f32 v[8:9], v[8:9], v[12:13]
	v_add_f32_e32 v12, 1.0, v14
	v_add_f32_e32 v13, 1.0, v15
	v_mul_f32_e32 v14, 0xbfb8aa3b, v4
	v_mul_f32_e32 v15, 0xbfb8aa3b, v5
	v_exp_f32_e32 v10, v10
	v_exp_f32_e32 v11, v11
	v_exp_f32_e32 v14, v14
	v_exp_f32_e32 v15, v15
	v_add_f32_e32 v10, 1.0, v10
	v_add_f32_e32 v11, 1.0, v11
	v_rcp_f32_e32 v12, v12
	v_rcp_f32_e32 v13, v13
	v_add_f32_e32 v14, 1.0, v14
	v_add_f32_e32 v15, 1.0, v15
	v_rcp_f32_e32 v10, v10
	v_rcp_f32_e32 v11, v11
	v_rcp_f32_e32 v14, v14
	v_rcp_f32_e32 v15, v15
	v_pk_mul_f32 v[6:7], v[6:7], v[12:13]
	v_pk_mul_f32 v[10:11], v[18:19], v[10:11]
	v_pk_mul_f32 v[6:7], v[6:7], s[50:51] op_sel_hi:[1,0]
	v_pk_mul_f32 v[4:5], v[4:5], v[14:15]
	v_lshl_add_u64 v[2:3], v[2:3], 1, s[20:21]
	v_pk_mul_f32 v[8:9], v[8:9], s[50:51] op_sel_hi:[1,0]
	v_pk_mul_f32 v[10:11], v[10:11], s[50:51] op_sel_hi:[1,0]
	v_pk_mul_f32 v[12:13], v[4:5], s[50:51] op_sel_hi:[1,0]
	v_cvt_pk_bf16_f32 v4, v10, v11
	v_cvt_pk_bf16_f32 v5, v8, v9
	v_cvt_pk_bf16_f32 v6, v6, v7
	s_nop 0
	v_cvt_pk_bf16_f32 v7, v12, v13
	global_store_dwordx4 v[2:3], v[4:7], off
	s_andn2_b64 vcc, exec, s[36:37]
	s_mov_b64 s[6:7], -1
	s_cbranch_vccnz .LBB0_324
.LBB0_484:
	s_branch .LBB0_323
.LBB0_486:
	s_cmp_gt_i32 s29, 2
	s_cbranch_scc0 .LBB0_490
	s_cmp_eq_u32 s29, 3
	s_mov_b64 s[86:87], -1
	s_cbranch_scc0 .LBB0_489
	v_mul_f32_e32 v186, 0xbfb8aa3b, v160
	v_exp_f32_e32 v186, v186
	v_mul_f32_e32 v187, 0xbfb8aa3b, v161
	v_exp_f32_e32 v187, v187
	v_mul_f32_e32 v189, 0xbfb8aa3b, v155
	v_add_f32_e32 v186, 1.0, v186
	v_rcp_f32_e32 v186, v186
	v_exp_f32_e32 v189, v189
	v_mul_f32_e32 v191, 0xbfb8aa3b, v157
	v_mul_f32_e32 v179, 0xbfb8aa3b, v158
	v_mul_f32_e32 v188, v160, v186
	v_add_f32_e32 v186, 1.0, v187
	v_mul_f32_e32 v187, 0xbfb8aa3b, v154
	v_rcp_f32_e32 v186, v186
	v_exp_f32_e32 v187, v187
	v_mul_f32_e32 v185, 0xbfb8aa3b, v159
	v_exp_f32_e32 v191, v191
	v_mul_f32_e32 v190, v161, v186
	v_add_f32_e32 v186, 1.0, v187
	v_add_f32_e32 v187, 1.0, v189
	v_mul_f32_e32 v189, 0xbfb8aa3b, v156
	v_exp_f32_e32 v189, v189
	v_exp_f32_e32 v179, v179
	v_exp_f32_e32 v185, v185
	v_add_f32_e32 v191, 1.0, v191
	v_add_f32_e32 v189, 1.0, v189
	v_add_f32_e32 v179, 1.0, v179
	v_add_f32_e32 v185, 1.0, v185
	v_rcp_f32_e32 v189, v189
	v_rcp_f32_e32 v191, v191
	v_rcp_f32_e32 v179, v179
	v_rcp_f32_e32 v185, v185
	v_rcp_f32_e32 v186, v186
	v_rcp_f32_e32 v187, v187
	v_mul_f32_e32 v189, v156, v189
	v_mul_f32_e32 v191, v157, v191
	v_mul_f32_e32 v179, v158, v179
	v_mul_f32_e32 v185, v159, v185
	v_mul_f32_e32 v192, v154, v186
	v_mul_f32_e32 v193, v155, v187
	v_cvt_pk_bf16_f32 v186, v179, v185
	v_cvt_pk_bf16_f32 v187, v188, v190
	v_cvt_pk_bf16_f32 v188, v192, v193
	v_cvt_pk_bf16_f32 v189, v189, v191
	v_lshl_add_u64 v[190:191], v[176:177], 1, s[22:23]
	global_store_dwordx4 v[190:191], v[186:189], off
	s_mov_b64 s[86:87], 0

;     __host__ __device__ __forceinline__ bool next(int i, Unit& u) const { const int vv = vid + (i / 5) * G; if (vv >= 256) return false; u.pm = vv >> 2; u.pn = (vv & 3) + 4 * (i % 5); return true; }
;     __host__ __device__ __forceinline__ bool next(int i, pg8::Unit& u) const { const long Lx = (long)i * G + c; if (Lx >= 128) return false; const int Lq = (int)Lx; u.pm = 8 * (Lq >> 5) + (Lq & 7); u.pn = (Lq >> 3) & 3; return true; }
;     __device__ __forceinline__ size_t b_off(const pg8::Unit& u) const { return (size_t)(u.pm >> 3) * 4 * 131072; }
;     ...
;     for (;;) {
;         const bool has_next = S.next(ui + 1, nxt);
;         const char* nA = has_next ? (const char*)g.A + (size_t)nxt.pm * tstepA + (size_t)nxt.pn * APN + kofA : cA; const char* nB = has_next ? (const char*)g.Bt + (size_t)nxt.pn * tstepB + S.b_off(nxt) + kofB : cB;
.LBB0_1120:
	s_andn2_b64 vcc, exec, s[6:7]
	s_mov_b32 s30, s72
	s_mov_b32 s28, s76
	s_mov_b64 s[36:37], s[96:97]
	s_mov_b64 s[34:35], s[78:79]
	s_cbranch_vccz .LBB0_1168
	s_branch .Lout_setup2

; #define PG8_BAR __builtin_amdgcn_s_barrier()
;     __device__ __forceinline__ size_t b_off(const pg8::Unit& u) const { return (size_t)(u.pm >> 3) * 4 * 131072; }
;     ...
;         const char* nA = has_next ? (const char*)g.A + (size_t)nxt.pm * tstepA + (size_t)nxt.pn * APN + kofA : cA; const char* nB = has_next ? (const char*)g.Bt + (size_t)nxt.pn * tstepB + S.b_off(nxt) + kofB : cB;
;         for (int t = 0; t < nt; t += 2) {
;             const bool last = (t == nt - 2);
;             const char* a1 = cA + (ptrdiff_t)(t + 1) * kstepA;
;             const char* a2 = last ? nA : cA + (ptrdiff_t)(t + 2) * kstepA; const char* b2 = last ? nB : cB + (ptrdiff_t)(t + 2) * kstep;
;             const char* a3 = a2 + kstepA; const char* b3 = b2 + kstep;
;             if (last && has_next) S.a_ready(nxt);
;     ...
;         if constexpr (ALIGN_EPI) { if (wr == 1) PG8_BAR; }
.Lout_s_1127:
	s_ashr_i32 s77, s76, 31
	s_lshl_b64 s[24:25], s[76:77], 20
	s_add_u32 s78, s33, s24
	s_addc_u32 s79, s40, s25
	s_and_b64 s[26:27], s[6:7], exec
	s_cselect_b32 s23, s79, s35
	s_cselect_b32 s29, s78, s34
	s_ashr_i32 s73, s72, 31
	s_lshl_b64 s[26:27], s[72:73], 20
	s_add_u32 s96, s41, s26
	s_addc_u32 s97, s48, s27
	s_and_b64 s[46:47], s[6:7], exec
	s_cselect_b32 s21, s97, s37
	s_cselect_b32 s31, s96, s36
	s_add_u32 s34, s34, 0xc000
	s_addc_u32 s35, s35, 0
	s_add_u32 s44, s36, 0x10000
	s_addc_u32 s56, s37, 0
	s_mov_b32 s57, -2
	s_cmp_eq_u64 s[8:9], 0
	s_cbranch_scc1 .Lout_nostg
	s_barrier
; #define PG8_STAGE(bufoff, gbase, voff) do { _Pragma("unroll") for (int _i = 0; _i < 2; ++_i) \
;         __builtin_amdgcn_global_load_lds((const unsigned*)((const char*)(gbase) + (voff)[_i]), (PG8_LAS unsigned*)(lds + (bufoff) + ldsw + _i * 8192), 16, 0, 0); } while (0)
; #define PG8_LDA(dst, b, h) do { _Pragma("unroll") for (int m = 0; m < 4; ++m) _Pragma("unroll") for (int k = 0; k < 2; ++k) dst[m][k] = *(const PG8_LAS bf16x8*)(lds + PG8_SA(b, h) + aoff + m * 2048 + k * 1024); } while (0)
; #define PG8_LDB(dst, b, h) do { _Pragma("unroll") for (int n = 0; n < 2; ++n) _Pragma("unroll") for (int k = 0; k < 2; ++k) dst[n][k] = *(const PG8_LAS bf16x8*)(lds + PG8_SB(b, h) + boff + n * 2048 + k * 1024); } while (0)
; #define PG8_MMA(ai, bj, At, Bt) do { __builtin_amdgcn_s_setprio(1); _Pragma("unroll") for (int m = 0; m < 4; ++m) _Pragma("unroll") for (int n = 0; n < 2; ++n) _Pragma("unroll") for (int k = 0; k < 2; ++k) \
;         acc[ai][bj][m][n] = __builtin_amdgcn_mfma_f32_16x16x32_bf16(Bt[n][k], At[m][k], acc[ai][bj][m][n], 0, 0, 0); __builtin_amdgcn_s_setprio(0); } while (0)
; #define PG8_WAIT_V(n) asm volatile("s_waitcnt vmcnt(" #n ")" ::: "memory")
; #define PG8_WAIT_L(n) asm volatile("s_waitcnt lgkmcnt(" #n ")" ::: "memory")
; #define PG8_BAR __builtin_amdgcn_s_barrier()
; #define PG8_SCHED __builtin_amdgcn_sched_barrier(0)
;     ...
;             PG8_LDB(B0, 0, 0); PG8_LDB(B1, 0, 1); PG8_SCHED; PG8_LDA(At, 0, 0); PG8_STAGE(PG8_SA(1, 1), a1 + hstepA, voffA);
;             PG8_WAIT_V(8); PG8_WAIT_L(0); PG8_BAR; PG8_MMA(0, 0, At, B0); PG8_MMA(0, 1, At, B1); PG8_BAR; PG8_SCHED;
;             PG8_LDA(At, 0, 1); PG8_STAGE(PG8_SB(0, 0), b2, voffB); PG8_STAGE(PG8_SB(0, 1), b2 + hstepB, voffB); PG8_STAGE(PG8_SA(0, 0), a2, voffA);
;             PG8_WAIT_V(8); PG8_WAIT_L(0); PG8_BAR; PG8_MMA(1, 0, At, B0); PG8_MMA(1, 1, At, B1); PG8_BAR; PG8_SCHED;
.Lout_nostg:
	s_add_u32 s36, s34, 0x4000
	s_addc_u32 s37, s35, 0
	s_cmp_eq_u32 s57, 28
	s_cselect_b32 s86, s29, s36
	s_cselect_b32 s87, s23, s37
	s_cselect_b32 s46, s31, s44
	s_cselect_b32 s47, s21, s56
	s_add_u32 s36, s86, 0x8000
	s_addc_u32 s37, s87, 0
	s_add_i32 s65, 0, 0x10000
	v_add_u32_e32 v0, s65, v242
	s_add_i32 s66, 0, 0x14000
	s_waitcnt lgkmcnt(0)
	ds_read_b128 v[130:133], v0
	ds_read_b128 v[134:137], v0 offset:1024
	ds_read_b128 v[138:141], v0 offset:2048
	ds_read_b128 v[142:145], v0 offset:3072
	v_add_u32_e32 v0, s66, v242
	ds_read_b128 v[146:149], v0
	ds_read_b128 v[150:153], v0 offset:1024
	ds_read_b128 v[154:157], v0 offset:2048
	ds_read_b128 v[158:161], v0 offset:3072
	s_add_i32 m0, s51, 0xc000
	ds_read_b128 v[162:165], v243
	ds_read_b128 v[166:169], v243 offset:1024
	ds_read_b128 v[170:173], v243 offset:2048
	ds_read_b128 v[174:177], v243 offset:3072
	ds_read_b128 v[178:181], v243 offset:4096
	ds_read_b128 v[182:185], v243 offset:5120
	ds_read_b128 v[198:201], v243 offset:6144
	ds_read_b128 v[202:205], v243 offset:7168
	global_load_lds_dwordx4 v194, s[34:35]
	s_add_i32 m0, s51, 0xe000
	s_nop 0
	global_load_lds_dwordx4 v196, s[34:35]
	s_waitcnt vmcnt(8)
	s_waitcnt lgkmcnt(0)
	s_barrier
	s_setprio 1
	s_waitcnt lgkmcnt(0)
	v_mfma_f32_16x16x32_bf16 v[126:129], v[130:133], v[162:165], 0
	v_mfma_f32_16x16x32_bf16 v[126:129], v[134:137], v[166:169], v[126:129]
	v_mfma_f32_16x16x32_bf16 v[122:125], v[142:145], v[166:169], 0
	v_mfma_f32_16x16x32_bf16 v[122:125], v[138:141], v[162:165], v[122:125]
	v_mfma_f32_16x16x32_bf16 v[106:109], v[138:141], v[170:173], 0
	v_mfma_f32_16x16x32_bf16 v[106:109], v[142:145], v[174:177], v[106:109]
	v_mfma_f32_16x16x32_bf16 v[110:113], v[134:137], v[174:177], 0
	v_mfma_f32_16x16x32_bf16 v[110:113], v[130:133], v[170:173], v[110:113]
	v_mfma_f32_16x16x32_bf16 v[94:97], v[130:133], v[178:181], 0
	v_mfma_f32_16x16x32_bf16 v[94:97], v[134:137], v[182:185], v[94:97]
	v_mfma_f32_16x16x32_bf16 v[90:93], v[142:145], v[182:185], 0
	v_mfma_f32_16x16x32_bf16 v[90:93], v[138:141], v[178:181], v[90:93]
	v_mfma_f32_16x16x32_bf16 v[74:77], v[138:141], v[198:201], 0
	v_mfma_f32_16x16x32_bf16 v[74:77], v[142:145], v[202:205], v[74:77]
	v_mfma_f32_16x16x32_bf16 v[78:81], v[134:137], v[202:205], 0
	v_mfma_f32_16x16x32_bf16 v[78:81], v[130:133], v[198:201], v[78:81]
	s_setprio 0
	s_setprio 1
	v_mfma_f32_16x16x32_bf16 v[118:121], v[146:149], v[162:165], 0
	v_mfma_f32_16x16x32_bf16 v[118:121], v[150:153], v[166:169], v[118:121]
	v_mfma_f32_16x16x32_bf16 v[114:117], v[158:161], v[166:169], 0
	v_mfma_f32_16x16x32_bf16 v[114:117], v[154:157], v[162:165], v[114:117]
	v_mfma_f32_16x16x32_bf16 v[98:101], v[154:157], v[170:173], 0
	v_mfma_f32_16x16x32_bf16 v[98:101], v[158:161], v[174:177], v[98:101]
	v_mfma_f32_16x16x32_bf16 v[102:105], v[150:153], v[174:177], 0
	v_mfma_f32_16x16x32_bf16 v[102:105], v[146:149], v[170:173], v[102:105]
	v_mfma_f32_16x16x32_bf16 v[86:89], v[146:149], v[178:181], 0
	v_mfma_f32_16x16x32_bf16 v[86:89], v[150:153], v[182:185], v[86:89]
	v_mfma_f32_16x16x32_bf16 v[82:85], v[158:161], v[182:185], 0
	v_mfma_f32_16x16x32_bf16 v[82:85], v[154:157], v[178:181], v[82:85]
	v_mfma_f32_16x16x32_bf16 v[66:69], v[154:157], v[198:201], 0
	v_mfma_f32_16x16x32_bf16 v[66:69], v[158:161], v[202:205], v[66:69]
	v_mfma_f32_16x16x32_bf16 v[70:73], v[150:153], v[202:205], 0
	v_mfma_f32_16x16x32_bf16 v[70:73], v[146:149], v[198:201], v[70:73]
	s_setprio 0
	s_barrier
	s_add_i32 s65, s65, s49
	s_mov_b32 m0, s65
	ds_read_b128 v[162:165], v243 offset:16384
	ds_read_b128 v[166:169], v243 offset:17408
	ds_read_b128 v[170:173], v243 offset:18432
	ds_read_b128 v[174:177], v243 offset:19456
	ds_read_b128 v[178:181], v243 offset:20480
	ds_read_b128 v[182:185], v243 offset:21504
	ds_read_b128 v[198:201], v243 offset:22528
	ds_read_b128 v[202:205], v243 offset:23552
	global_load_lds_dwordx4 v188, s[46:47]
	s_add_i32 m0, s65, 0x2000
	s_add_u32 s90, s46, 0x4000
	s_addc_u32 s91, s47, 0
	s_add_i32 s65, s66, s49
	global_load_lds_dwordx4 v192, s[46:47]
	s_mov_b32 m0, s65
	s_nop 0
	global_load_lds_dwordx4 v188, s[90:91]
	s_add_i32 m0, s65, 0x2000
	s_nop 0
	global_load_lds_dwordx4 v192, s[90:91]
	s_mov_b32 m0, s51
	s_nop 0
	global_load_lds_dwordx4 v186, s[86:87]
	s_mov_b32 m0, s54
	s_nop 0
	global_load_lds_dwordx4 v190, s[86:87]
	s_waitcnt vmcnt(8)
	s_waitcnt lgkmcnt(0)
	s_barrier
	s_setprio 1
	s_waitcnt lgkmcnt(0)
	v_mfma_f32_16x16x32_bf16 v[62:65], v[130:133], v[162:165], 0
	v_mfma_f32_16x16x32_bf16 v[62:65], v[134:137], v[166:169], v[62:65]
	v_mfma_f32_16x16x32_bf16 v[58:61], v[142:145], v[166:169], 0
	v_mfma_f32_16x16x32_bf16 v[58:61], v[138:141], v[162:165], v[58:61]
	v_mfma_f32_16x16x32_bf16 v[42:45], v[138:141], v[170:173], 0
	v_mfma_f32_16x16x32_bf16 v[42:45], v[142:145], v[174:177], v[42:45]
	v_mfma_f32_16x16x32_bf16 v[46:49], v[134:137], v[174:177], 0
	v_mfma_f32_16x16x32_bf16 v[46:49], v[130:133], v[170:173], v[46:49]
	v_mfma_f32_16x16x32_bf16 v[30:33], v[130:133], v[178:181], 0
	v_mfma_f32_16x16x32_bf16 v[30:33], v[134:137], v[182:185], v[30:33]
	v_mfma_f32_16x16x32_bf16 v[26:29], v[142:145], v[182:185], 0
	v_mfma_f32_16x16x32_bf16 v[26:29], v[138:141], v[178:181], v[26:29]
	v_mfma_f32_16x16x32_bf16 v[10:13], v[138:141], v[198:201], 0
	v_mfma_f32_16x16x32_bf16 v[10:13], v[142:145], v[202:205], v[10:13]
	v_mfma_f32_16x16x32_bf16 v[14:17], v[134:137], v[202:205], 0
	v_mfma_f32_16x16x32_bf16 v[14:17], v[130:133], v[198:201], v[14:17]
	s_setprio 0
	s_setprio 1
	v_mfma_f32_16x16x32_bf16 v[54:57], v[146:149], v[162:165], 0
	v_mfma_f32_16x16x32_bf16 v[54:57], v[150:153], v[166:169], v[54:57]
	v_mfma_f32_16x16x32_bf16 v[50:53], v[158:161], v[166:169], 0
	v_mfma_f32_16x16x32_bf16 v[50:53], v[154:157], v[162:165], v[50:53]
	v_mfma_f32_16x16x32_bf16 v[34:37], v[154:157], v[170:173], 0
	v_mfma_f32_16x16x32_bf16 v[34:37], v[158:161], v[174:177], v[34:37]
	v_mfma_f32_16x16x32_bf16 v[38:41], v[150:153], v[174:177], 0
	v_mfma_f32_16x16x32_bf16 v[38:41], v[146:149], v[170:173], v[38:41]
	v_mfma_f32_16x16x32_bf16 v[22:25], v[146:149], v[178:181], 0
	v_mfma_f32_16x16x32_bf16 v[22:25], v[150:153], v[182:185], v[22:25]
	v_mfma_f32_16x16x32_bf16 v[18:21], v[158:161], v[182:185], 0
	v_mfma_f32_16x16x32_bf16 v[18:21], v[154:157], v[178:181], v[18:21]
	v_mfma_f32_16x16x32_bf16 v[2:5], v[154:157], v[198:201], 0
	v_mfma_f32_16x16x32_bf16 v[2:5], v[158:161], v[202:205], v[2:5]
	v_mfma_f32_16x16x32_bf16 v[6:9], v[150:153], v[202:205], 0
	v_mfma_f32_16x16x32_bf16 v[6:9], v[146:149], v[198:201], v[6:9]
	s_setprio 0
	s_barrier
	s_branch .Lout_mid

; #define PG8_STAGE(bufoff, gbase, voff) do { _Pragma("unroll") for (int _i = 0; _i < 2; ++_i) \
;         __builtin_amdgcn_global_load_lds((const unsigned*)((const char*)(gbase) + (voff)[_i]), (PG8_LAS unsigned*)(lds + (bufoff) + ldsw + _i * 8192), 16, 0, 0); } while (0)
; #define PG8_LDA(dst, b, h) do { _Pragma("unroll") for (int m = 0; m < 4; ++m) _Pragma("unroll") for (int k = 0; k < 2; ++k) dst[m][k] = *(const PG8_LAS bf16x8*)(lds + PG8_SA(b, h) + aoff + m * 2048 + k * 1024); } while (0)
; #define PG8_LDB(dst, b, h) do { _Pragma("unroll") for (int n = 0; n < 2; ++n) _Pragma("unroll") for (int k = 0; k < 2; ++k) dst[n][k] = *(const PG8_LAS bf16x8*)(lds + PG8_SB(b, h) + boff + n * 2048 + k * 1024); } while (0)
; #define PG8_MMA(ai, bj, At, Bt) do { __builtin_amdgcn_s_setprio(1); _Pragma("unroll") for (int m = 0; m < 4; ++m) _Pragma("unroll") for (int n = 0; n < 2; ++n) _Pragma("unroll") for (int k = 0; k < 2; ++k) \
;         acc[ai][bj][m][n] = __builtin_amdgcn_mfma_f32_16x16x32_bf16(Bt[n][k], At[m][k], acc[ai][bj][m][n], 0, 0, 0); __builtin_amdgcn_s_setprio(0); } while (0)
; #define PG8_WAIT_V(n) asm volatile("s_waitcnt vmcnt(" #n ")" ::: "memory")
; #define PG8_WAIT_L(n) asm volatile("s_waitcnt lgkmcnt(" #n ")" ::: "memory")
; #define PG8_BAR __builtin_amdgcn_s_barrier()
; #define PG8_SCHED __builtin_amdgcn_sched_barrier(0)
;     ...
;             PG8_LDB(B0, 1, 0); PG8_LDB(B1, 1, 1); PG8_SCHED; PG8_LDA(At, 1, 0); PG8_STAGE(PG8_SA(0, 1), a2 + hstepA, voffA);
;             PG8_WAIT_V(8); PG8_WAIT_L(0); PG8_BAR; PG8_MMA(0, 0, At, B0); PG8_MMA(0, 1, At, B1); PG8_BAR; PG8_SCHED;
;             PG8_LDA(At, 1, 1); PG8_STAGE(PG8_SB(1, 0), b3, voffB); PG8_STAGE(PG8_SB(1, 1), b3 + hstepB, voffB); PG8_STAGE(PG8_SA(1, 0), a3, voffA);
;             PG8_WAIT_V(8); PG8_WAIT_L(0); PG8_BAR; PG8_MMA(1, 0, At, B0); PG8_MMA(1, 1, At, B1); PG8_BAR; PG8_SCHED;
.Lout_mid:
	s_add_i32 s65, 0, 0x18000
	v_add_u32_e32 v0, s65, v242
	s_add_i32 s66, 0, 0x1c000
	ds_read_b128 v[130:133], v0
	ds_read_b128 v[134:137], v0 offset:1024
	ds_read_b128 v[138:141], v0 offset:2048
	ds_read_b128 v[142:145], v0 offset:3072
	v_add_u32_e32 v0, s66, v242
	ds_read_b128 v[146:149], v0
	ds_read_b128 v[150:153], v0 offset:1024
	ds_read_b128 v[154:157], v0 offset:2048
	ds_read_b128 v[158:161], v0 offset:3072
	s_add_u32 s86, s86, 0x4000
	s_addc_u32 s87, s87, 0
	s_mov_b32 m0, s55
	ds_read_b128 v[162:165], v243 offset:32768
	ds_read_b128 v[166:169], v243 offset:33792
	ds_read_b128 v[170:173], v243 offset:34816
	ds_read_b128 v[174:177], v243 offset:35840
	ds_read_b128 v[178:181], v243 offset:36864
	ds_read_b128 v[182:185], v243 offset:37888
	ds_read_b128 v[198:201], v243 offset:38912
	ds_read_b128 v[202:205], v243 offset:39936
	global_load_lds_dwordx4 v186, s[86:87]
	s_mov_b32 m0, s61
	s_nop 0
	global_load_lds_dwordx4 v190, s[86:87]
	s_waitcnt vmcnt(8)
	s_waitcnt lgkmcnt(0)
	s_barrier
	s_setprio 1
	s_waitcnt lgkmcnt(0)
	v_mfma_f32_16x16x32_bf16 v[126:129], v[130:133], v[162:165], v[126:129]
	v_mfma_f32_16x16x32_bf16 v[126:129], v[134:137], v[166:169], v[126:129]
	v_mfma_f32_16x16x32_bf16 v[122:125], v[142:145], v[166:169], v[122:125]
	v_mfma_f32_16x16x32_bf16 v[122:125], v[138:141], v[162:165], v[122:125]
	v_mfma_f32_16x16x32_bf16 v[106:109], v[138:141], v[170:173], v[106:109]
	v_mfma_f32_16x16x32_bf16 v[106:109], v[142:145], v[174:177], v[106:109]
	v_mfma_f32_16x16x32_bf16 v[110:113], v[134:137], v[174:177], v[110:113]
	v_mfma_f32_16x16x32_bf16 v[110:113], v[130:133], v[170:173], v[110:113]
	v_mfma_f32_16x16x32_bf16 v[94:97], v[130:133], v[178:181], v[94:97]
	v_mfma_f32_16x16x32_bf16 v[94:97], v[134:137], v[182:185], v[94:97]
	v_mfma_f32_16x16x32_bf16 v[90:93], v[142:145], v[182:185], v[90:93]
	v_mfma_f32_16x16x32_bf16 v[90:93], v[138:141], v[178:181], v[90:93]
	v_mfma_f32_16x16x32_bf16 v[74:77], v[138:141], v[198:201], v[74:77]
	v_mfma_f32_16x16x32_bf16 v[74:77], v[142:145], v[202:205], v[74:77]
	v_mfma_f32_16x16x32_bf16 v[78:81], v[134:137], v[202:205], v[78:81]
	v_mfma_f32_16x16x32_bf16 v[78:81], v[130:133], v[198:201], v[78:81]
	s_setprio 0
	s_setprio 1
	v_mfma_f32_16x16x32_bf16 v[118:121], v[146:149], v[162:165], v[118:121]
	v_mfma_f32_16x16x32_bf16 v[118:121], v[150:153], v[166:169], v[118:121]
	v_mfma_f32_16x16x32_bf16 v[114:117], v[158:161], v[166:169], v[114:117]
	v_mfma_f32_16x16x32_bf16 v[114:117], v[154:157], v[162:165], v[114:117]
	v_mfma_f32_16x16x32_bf16 v[98:101], v[154:157], v[170:173], v[98:101]
	v_mfma_f32_16x16x32_bf16 v[98:101], v[158:161], v[174:177], v[98:101]
	v_mfma_f32_16x16x32_bf16 v[102:105], v[150:153], v[174:177], v[102:105]
	v_mfma_f32_16x16x32_bf16 v[102:105], v[146:149], v[170:173], v[102:105]
	v_mfma_f32_16x16x32_bf16 v[86:89], v[146:149], v[178:181], v[86:89]
	v_mfma_f32_16x16x32_bf16 v[86:89], v[150:153], v[182:185], v[86:89]
	v_mfma_f32_16x16x32_bf16 v[82:85], v[158:161], v[182:185], v[82:85]
	v_mfma_f32_16x16x32_bf16 v[82:85], v[154:157], v[178:181], v[82:85]
	v_mfma_f32_16x16x32_bf16 v[66:69], v[154:157], v[198:201], v[66:69]
	v_mfma_f32_16x16x32_bf16 v[66:69], v[158:161], v[202:205], v[66:69]
	v_mfma_f32_16x16x32_bf16 v[70:73], v[150:153], v[202:205], v[70:73]
	v_mfma_f32_16x16x32_bf16 v[70:73], v[146:149], v[198:201], v[70:73]
	s_setprio 0
	s_barrier
	s_add_u32 s86, s46, 0x8000
	s_addc_u32 s87, s47, 0
	s_add_i32 s65, s65, s49
	s_mov_b32 m0, s65
	ds_read_b128 v[162:165], v243 offset:49152
	ds_read_b128 v[166:169], v243 offset:50176
	ds_read_b128 v[170:173], v243 offset:51200
	ds_read_b128 v[174:177], v243 offset:52224
	ds_read_b128 v[178:181], v243 offset:53248
	ds_read_b128 v[182:185], v243 offset:54272
	ds_read_b128 v[198:201], v243 offset:55296
	ds_read_b128 v[202:205], v243 offset:56320
	global_load_lds_dwordx4 v188, s[86:87]
	s_add_i32 m0, s65, 0x2000
	s_add_u32 s46, s46, 0xc000
	s_addc_u32 s47, s47, 0
	s_add_i32 s65, s66, s49
	global_load_lds_dwordx4 v192, s[86:87]
	s_mov_b32 m0, s65
	s_nop 0
	global_load_lds_dwordx4 v188, s[46:47]
	s_add_i32 m0, s65, 0x2000
	s_nop 0
	global_load_lds_dwordx4 v192, s[46:47]
	s_mov_b32 m0, s83
	s_nop 0
	global_load_lds_dwordx4 v186, s[36:37]
	v_lshl_add_u64 v[206:207], s[36:37], 0, v[190:191]
	s_mov_b32 m0, s85
	s_nop 0
	global_load_lds_dwordx4 v[206:207], off
	s_waitcnt vmcnt(8)
	s_waitcnt lgkmcnt(0)
	s_barrier
	s_setprio 1
	s_waitcnt lgkmcnt(0)
	v_mfma_f32_16x16x32_bf16 v[62:65], v[130:133], v[162:165], v[62:65]
	v_mfma_f32_16x16x32_bf16 v[62:65], v[134:137], v[166:169], v[62:65]
	v_mfma_f32_16x16x32_bf16 v[58:61], v[142:145], v[166:169], v[58:61]
	v_mfma_f32_16x16x32_bf16 v[58:61], v[138:141], v[162:165], v[58:61]
	v_mfma_f32_16x16x32_bf16 v[42:45], v[138:141], v[170:173], v[42:45]
	v_mfma_f32_16x16x32_bf16 v[42:45], v[142:145], v[174:177], v[42:45]
	v_mfma_f32_16x16x32_bf16 v[46:49], v[134:137], v[174:177], v[46:49]
	v_mfma_f32_16x16x32_bf16 v[46:49], v[130:133], v[170:173], v[46:49]
	v_mfma_f32_16x16x32_bf16 v[30:33], v[130:133], v[178:181], v[30:33]
	v_mfma_f32_16x16x32_bf16 v[30:33], v[134:137], v[182:185], v[30:33]
	v_mfma_f32_16x16x32_bf16 v[26:29], v[142:145], v[182:185], v[26:29]
	v_mfma_f32_16x16x32_bf16 v[26:29], v[138:141], v[178:181], v[26:29]
	v_mfma_f32_16x16x32_bf16 v[10:13], v[138:141], v[198:201], v[10:13]
	v_mfma_f32_16x16x32_bf16 v[10:13], v[142:145], v[202:205], v[10:13]
	v_mfma_f32_16x16x32_bf16 v[14:17], v[134:137], v[202:205], v[14:17]
	v_mfma_f32_16x16x32_bf16 v[14:17], v[130:133], v[198:201], v[14:17]
	s_setprio 0
	s_setprio 1
	v_mfma_f32_16x16x32_bf16 v[54:57], v[146:149], v[162:165], v[54:57]
	v_mfma_f32_16x16x32_bf16 v[54:57], v[150:153], v[166:169], v[54:57]
	v_mfma_f32_16x16x32_bf16 v[50:53], v[158:161], v[166:169], v[50:53]
	v_mfma_f32_16x16x32_bf16 v[50:53], v[154:157], v[162:165], v[50:53]
	v_mfma_f32_16x16x32_bf16 v[34:37], v[154:157], v[170:173], v[34:37]
	v_mfma_f32_16x16x32_bf16 v[34:37], v[158:161], v[174:177], v[34:37]
	v_mfma_f32_16x16x32_bf16 v[38:41], v[150:153], v[174:177], v[38:41]
	v_mfma_f32_16x16x32_bf16 v[38:41], v[146:149], v[170:173], v[38:41]
	v_mfma_f32_16x16x32_bf16 v[22:25], v[146:149], v[178:181], v[22:25]
	v_mfma_f32_16x16x32_bf16 v[22:25], v[150:153], v[182:185], v[22:25]
	v_mfma_f32_16x16x32_bf16 v[18:21], v[158:161], v[182:185], v[18:21]
	v_mfma_f32_16x16x32_bf16 v[18:21], v[154:157], v[178:181], v[18:21]
	v_mfma_f32_16x16x32_bf16 v[2:5], v[154:157], v[198:201], v[2:5]
	v_mfma_f32_16x16x32_bf16 v[2:5], v[158:161], v[202:205], v[2:5]
	v_mfma_f32_16x16x32_bf16 v[6:9], v[150:153], v[202:205], v[6:9]
	v_mfma_f32_16x16x32_bf16 v[6:9], v[146:149], v[198:201], v[6:9]
	s_setprio 0
	s_barrier
	s_add_i32 s57, s57, 2
	s_add_u32 s34, s34, 0x10000
	s_addc_u32 s35, s35, 0
	s_add_u32 s44, s44, 0x10000
	s_addc_u32 s56, s56, 0
	s_cmp_gt_u32 s57, 29
	s_cbranch_scc0 .LBB0_1128
	s_and_b64 vcc, exec, s[92:93]
	s_cbranch_vccz .LBB0_1131
	s_barrier

; #define PG8_WAIT_V(n) asm volatile("s_waitcnt vmcnt(" #n ")" ::: "memory")
; #define PG8_BAR __builtin_amdgcn_s_barrier()
;     ...
;         if constexpr (ALIGN_EPI) { if (wr == 1) PG8_BAR; }
;     }
;     PG8_WAIT_V(0);
;     if constexpr (!ALIGN_EPI) { if (wr == 0) PG8_BAR; }
;     PG8_BAR;
.LBB0_1166:
	s_branch .LBB0_1119
.LBB0_1168:
	s_waitcnt vmcnt(0)
	v_readlane_b32 s70, v254, 54
	v_readlane_b32 s71, v254, 55
	v_readlane_b32 s72, v254, 0
	v_readlane_b32 s42, v254, 62
	v_readlane_b32 s73, v254, 1
	v_readlane_b32 s74, v254, 2
	v_readlane_b32 s75, v254, 3
	v_readlane_b32 s76, v254, 4
	v_readlane_b32 s77, v254, 5
	v_readlane_b32 s78, v254, 6
	v_readlane_b32 s79, v254, 7
	v_readlane_b32 s43, v254, 63
	v_readlane_b32 s93, v254, 57
	v_readlane_b32 s94, v254, 58
	v_readlane_b32 s95, v254, 59
	v_readlane_b32 s56, v254, 60
	v_readlane_b32 s57, v254, 61
	s_movk_i32 s65, 0x2000
	s_mov_b32 s66, 0x10000
	s_movk_i32 s71, 0x6000
	s_movk_i32 s92, 0x1080
	s_movk_i32 s80, 0x3000
	s_movk_i32 s81, 0x7000
	s_mov_b32 s55, 0x2e8ba2e9
	v_readlane_b32 s48, v255, 0
	v_readlane_b32 s63, v254, 56
	v_mov_b32_e32 v240, 0x358637bd
	v_mov_b32_e32 v241, 1
	v_mov_b32_e32 v242, 0x41b17218
	v_bfrev_b32_e32 v243, 0.5
	s_barrier
	v_readlane_b32 s49, v255, 1
	s_add_i32 s2, s69, 8
	s_cmp_ge_i32 s2, s79
	s_cbranch_scc1 .LBB0_1238

;     __host__ __device__ __forceinline__ bool next(int i, Unit& u) const { const int vv = vid + (i / 5) * G; if (vv >= 256) return false; u.pm = vv >> 2; u.pn = (vv & 3) + 4 * (i % 5); return true; }
;     __host__ __device__ __forceinline__ bool next(int i, pg8::Unit& u) const { const long Lx = (long)i * G + c; if (Lx >= 128) return false; const int Lq = (int)Lx; u.pm = 8 * (Lq >> 5) + (Lq & 7); u.pn = (Lq >> 3) & 3; return true; }
;     __device__ __forceinline__ size_t b_off(const pg8::Unit& u) const { return (size_t)(u.pm >> 3) * 4 * 131072; }
;     ...
;     for (;;) {
;         const bool has_next = S.next(ui + 1, nxt);
;         const char* nA = has_next ? (const char*)g.A + (size_t)nxt.pm * tstepA + (size_t)nxt.pn * APN + kofA : cA; const char* nB = has_next ? (const char*)g.Bt + (size_t)nxt.pn * tstepB + S.b_off(nxt) + kofB : cB;
.LBB0_1252:
	s_andn2_b64 vcc, exec, s[10:11]
	s_mov_b32 s11, s24
	s_mov_b32 s10, s26
	s_mov_b64 s[36:37], s[30:31]
	s_mov_b64 s[34:35], s[28:29]
	s_mov_b32 s92, s56
	s_cbranch_vccz .LBB0_1268
	s_branch .Lup_setup2

;     __device__ __forceinline__ size_t b_off(const pg8::Unit& u) const { return (size_t)(u.pm >> 3) * 4 * 131072; }
;     ...
;         const char* nA = has_next ? (const char*)g.A + (size_t)nxt.pm * tstepA + (size_t)nxt.pn * APN + kofA : cA; const char* nB = has_next ? (const char*)g.Bt + (size_t)nxt.pn * tstepB + S.b_off(nxt) + kofB : cB;
;         for (int t = 0; t < nt; t += 2) {
;             const bool last = (t == nt - 2);
;             const char* a1 = cA + (ptrdiff_t)(t + 1) * kstepA;
;             const char* a2 = last ? nA : cA + (ptrdiff_t)(t + 2) * kstepA; const char* b2 = last ? nB : cB + (ptrdiff_t)(t + 2) * kstep;
;             const char* a3 = a2 + kstepA; const char* b3 = b2 + kstep;
;             if (last && has_next) S.a_ready(nxt);
.Lup_s_1255:
	s_ashr_i32 s27, s26, 31
	s_lshl_b64 s[28:29], s[26:27], 20
	s_add_u32 s28, s2, s28
	s_addc_u32 s29, s33, s29
	s_and_b64 s[30:31], s[6:7], exec
	s_cselect_b32 s27, s29, s35
	s_cselect_b32 s57, s28, s34
	s_ashr_i32 s25, s24, 31
	s_lshl_b64 s[30:31], s[24:25], 20
	s_add_u32 s30, s40, s30
	s_addc_u32 s31, s41, s31
	s_and_b64 s[46:47], s[6:7], exec
	s_cselect_b32 s25, s31, s37
	s_cselect_b32 vcc_lo, s30, s36
	s_add_u32 vcc_hi, s36, 0x10000
	s_addc_u32 s65, s37, 0
	s_mov_b32 s66, -2
	s_cmp_eq_u64 s[12:13], 0
	s_cbranch_scc1 .Lup_nostg
	s_barrier
; #define PG8_STAGE(bufoff, gbase, voff) do { _Pragma("unroll") for (int _i = 0; _i < 2; ++_i) \
;         __builtin_amdgcn_global_load_lds((const unsigned*)((const char*)(gbase) + (voff)[_i]), (PG8_LAS unsigned*)(lds + (bufoff) + ldsw + _i * 8192), 16, 0, 0); } while (0)
; #define PG8_LDA(dst, b, h) do { _Pragma("unroll") for (int m = 0; m < 4; ++m) _Pragma("unroll") for (int k = 0; k < 2; ++k) dst[m][k] = *(const PG8_LAS bf16x8*)(lds + PG8_SA(b, h) + aoff + m * 2048 + k * 1024); } while (0)
; #define PG8_LDB(dst, b, h) do { _Pragma("unroll") for (int n = 0; n < 2; ++n) _Pragma("unroll") for (int k = 0; k < 2; ++k) dst[n][k] = *(const PG8_LAS bf16x8*)(lds + PG8_SB(b, h) + boff + n * 2048 + k * 1024); } while (0)
; #define PG8_MMA(ai, bj, At, Bt) do { __builtin_amdgcn_s_setprio(1); _Pragma("unroll") for (int m = 0; m < 4; ++m) _Pragma("unroll") for (int n = 0; n < 2; ++n) _Pragma("unroll") for (int k = 0; k < 2; ++k) \
;         acc[ai][bj][m][n] = __builtin_amdgcn_mfma_f32_16x16x32_bf16(Bt[n][k], At[m][k], acc[ai][bj][m][n], 0, 0, 0); __builtin_amdgcn_s_setprio(0); } while (0)
; #define PG8_WAIT_V(n) asm volatile("s_waitcnt vmcnt(" #n ")" ::: "memory")
; #define PG8_WAIT_L(n) asm volatile("s_waitcnt lgkmcnt(" #n ")" ::: "memory")
; #define PG8_BAR __builtin_amdgcn_s_barrier()
; #define PG8_SCHED __builtin_amdgcn_sched_barrier(0)
;     ...
;             PG8_LDB(B0, 0, 0); PG8_LDB(B1, 0, 1); PG8_SCHED; PG8_LDA(At, 0, 0); PG8_STAGE(PG8_SA(1, 1), a1 + hstepA, voffA);
;             PG8_WAIT_V(8); PG8_WAIT_L(0); PG8_BAR; PG8_MMA(0, 0, At, B0); PG8_MMA(0, 1, At, B1); PG8_BAR; PG8_SCHED;
;             PG8_LDA(At, 0, 1); PG8_STAGE(PG8_SB(0, 0), b2, voffB); PG8_STAGE(PG8_SB(0, 1), b2 + hstepB, voffB); PG8_STAGE(PG8_SA(0, 0), a2, voffA);
;             PG8_WAIT_V(8); PG8_WAIT_L(0); PG8_BAR; PG8_MMA(1, 0, At, B0); PG8_MMA(1, 1, At, B1); PG8_BAR; PG8_SCHED;
.Lup_nostg:
	s_add_u32 s36, s34, 0x10000
	s_addc_u32 s37, s35, 0
	s_cmp_eq_u32 s66, 28
	s_cselect_b32 s88, s57, s36
	s_cselect_b32 s89, s27, s37
	s_cselect_b32 s86, vcc_lo, vcc_hi
	s_cselect_b32 s87, s25, s65
	s_add_u32 s46, s88, 0x8000
	s_addc_u32 s47, s89, 0
	s_add_i32 s96, 0, 0x10000
	v_add_u32_e32 v0, s96, v192
	s_add_i32 s97, 0, 0x14000
	ds_read_b128 v[130:133], v0
	ds_read_b128 v[134:137], v0 offset:1024
	ds_read_b128 v[138:141], v0 offset:2048
	ds_read_b128 v[142:145], v0 offset:3072
	v_add_u32_e32 v0, s97, v192
	ds_read_b128 v[146:149], v0
	ds_read_b128 v[150:153], v0 offset:1024
	ds_read_b128 v[154:157], v0 offset:2048
	ds_read_b128 v[170:173], v0 offset:3072
	s_add_i32 m0, s48, 0xc000
	ds_read_b128 v[174:177], v193
	ds_read_b128 v[178:181], v193 offset:1024
	ds_read_b128 v[182:185], v193 offset:2048
	ds_read_b128 v[186:189], v193 offset:3072
	ds_read_b128 v[194:197], v193 offset:4096
	ds_read_b128 v[198:201], v193 offset:5120
	ds_read_b128 v[202:205], v193 offset:6144
	ds_read_b128 v[206:209], v193 offset:7168
	global_load_lds_dwordx4 v166, s[34:35]
	s_add_i32 m0, s48, 0xe000
	s_nop 0
	global_load_lds_dwordx4 v168, s[34:35]
	s_waitcnt vmcnt(8)
	s_waitcnt lgkmcnt(0)
	s_barrier
	s_setprio 1
	s_waitcnt lgkmcnt(0)
	v_mfma_f32_16x16x32_bf16 v[126:129], v[130:133], v[174:177], 0
	v_mfma_f32_16x16x32_bf16 v[126:129], v[134:137], v[178:181], v[126:129]
	v_mfma_f32_16x16x32_bf16 v[122:125], v[142:145], v[178:181], 0
	v_mfma_f32_16x16x32_bf16 v[122:125], v[138:141], v[174:177], v[122:125]
	v_mfma_f32_16x16x32_bf16 v[114:117], v[138:141], v[182:185], 0
	v_mfma_f32_16x16x32_bf16 v[114:117], v[142:145], v[186:189], v[114:117]
	v_mfma_f32_16x16x32_bf16 v[118:121], v[134:137], v[186:189], 0
	v_mfma_f32_16x16x32_bf16 v[118:121], v[130:133], v[182:185], v[118:121]
	v_mfma_f32_16x16x32_bf16 v[110:113], v[130:133], v[194:197], 0
	v_mfma_f32_16x16x32_bf16 v[110:113], v[134:137], v[198:201], v[110:113]
	v_mfma_f32_16x16x32_bf16 v[106:109], v[142:145], v[198:201], 0
	v_mfma_f32_16x16x32_bf16 v[106:109], v[138:141], v[194:197], v[106:109]
	v_mfma_f32_16x16x32_bf16 v[98:101], v[138:141], v[202:205], 0
	v_mfma_f32_16x16x32_bf16 v[98:101], v[142:145], v[206:209], v[98:101]
	v_mfma_f32_16x16x32_bf16 v[102:105], v[134:137], v[206:209], 0
	v_mfma_f32_16x16x32_bf16 v[102:105], v[130:133], v[202:205], v[102:105]
	s_setprio 0
	s_setprio 1
	v_mfma_f32_16x16x32_bf16 v[30:33], v[146:149], v[174:177], 0
	v_mfma_f32_16x16x32_bf16 v[30:33], v[150:153], v[178:181], v[30:33]
	v_mfma_f32_16x16x32_bf16 v[46:49], v[170:173], v[178:181], 0
	v_mfma_f32_16x16x32_bf16 v[46:49], v[154:157], v[174:177], v[46:49]
	v_mfma_f32_16x16x32_bf16 v[34:37], v[154:157], v[182:185], 0
	v_mfma_f32_16x16x32_bf16 v[34:37], v[170:173], v[186:189], v[34:37]
	v_mfma_f32_16x16x32_bf16 v[26:29], v[150:153], v[186:189], 0
	v_mfma_f32_16x16x32_bf16 v[26:29], v[146:149], v[182:185], v[26:29]
	v_mfma_f32_16x16x32_bf16 v[94:97], v[146:149], v[194:197], 0
	v_mfma_f32_16x16x32_bf16 v[94:97], v[150:153], v[198:201], v[94:97]
	v_mfma_f32_16x16x32_bf16 v[90:93], v[170:173], v[198:201], 0
	v_mfma_f32_16x16x32_bf16 v[90:93], v[154:157], v[194:197], v[90:93]
	v_mfma_f32_16x16x32_bf16 v[82:85], v[154:157], v[202:205], 0
	v_mfma_f32_16x16x32_bf16 v[82:85], v[170:173], v[206:209], v[82:85]
	v_mfma_f32_16x16x32_bf16 v[86:89], v[150:153], v[206:209], 0
	v_mfma_f32_16x16x32_bf16 v[86:89], v[146:149], v[202:205], v[86:89]
	s_setprio 0
	s_barrier
	s_add_i32 s34, s96, s44
	s_mov_b32 m0, s34
	ds_read_b128 v[174:177], v193 offset:16384
	ds_read_b128 v[178:181], v193 offset:17408
	ds_read_b128 v[182:185], v193 offset:18432
	ds_read_b128 v[186:189], v193 offset:19456
	ds_read_b128 v[194:197], v193 offset:20480
	ds_read_b128 v[198:201], v193 offset:21504
	ds_read_b128 v[202:205], v193 offset:22528
	ds_read_b128 v[206:209], v193 offset:23552
	global_load_lds_dwordx4 v162, s[86:87]
	s_add_i32 m0, s34, 0x2000
	s_add_u32 s34, s86, 0x4000
	s_addc_u32 s35, s87, 0
	s_add_i32 s96, s97, s44
	global_load_lds_dwordx4 v158, s[86:87]
	s_mov_b32 m0, s96
	v_lshl_add_u64 v[210:211], s[88:89], 0, v[160:161]
	global_load_lds_dwordx4 v162, s[34:35]
	s_add_i32 m0, s96, 0x2000
	s_nop 0
	global_load_lds_dwordx4 v158, s[34:35]
	v_lshl_add_u64 v[190:191], s[88:89], 0, v[164:165]
	s_mov_b32 m0, s48
	s_nop 0
	global_load_lds_dwordx4 v[190:191], off
	s_mov_b32 m0, s49
	s_nop 0
	global_load_lds_dwordx4 v[210:211], off
	s_waitcnt vmcnt(8)
	s_waitcnt lgkmcnt(0)
	s_barrier
	s_setprio 1
	s_waitcnt lgkmcnt(0)
	v_mfma_f32_16x16x32_bf16 v[78:81], v[130:133], v[174:177], 0
	v_mfma_f32_16x16x32_bf16 v[78:81], v[134:137], v[178:181], v[78:81]
	v_mfma_f32_16x16x32_bf16 v[74:77], v[142:145], v[178:181], 0
	v_mfma_f32_16x16x32_bf16 v[74:77], v[138:141], v[174:177], v[74:77]
	v_mfma_f32_16x16x32_bf16 v[66:69], v[138:141], v[182:185], 0
	v_mfma_f32_16x16x32_bf16 v[66:69], v[142:145], v[186:189], v[66:69]
	v_mfma_f32_16x16x32_bf16 v[70:73], v[134:137], v[186:189], 0
	v_mfma_f32_16x16x32_bf16 v[70:73], v[130:133], v[182:185], v[70:73]
	v_mfma_f32_16x16x32_bf16 v[42:45], v[130:133], v[194:197], 0
	v_mfma_f32_16x16x32_bf16 v[42:45], v[134:137], v[198:201], v[42:45]
	v_mfma_f32_16x16x32_bf16 v[6:9], v[142:145], v[198:201], 0
	v_mfma_f32_16x16x32_bf16 v[6:9], v[138:141], v[194:197], v[6:9]
	v_mfma_f32_16x16x32_bf16 v[2:5], v[138:141], v[202:205], 0
	v_mfma_f32_16x16x32_bf16 v[2:5], v[142:145], v[206:209], v[2:5]
	v_mfma_f32_16x16x32_bf16 v[38:41], v[134:137], v[206:209], 0
	v_mfma_f32_16x16x32_bf16 v[38:41], v[130:133], v[202:205], v[38:41]
	s_setprio 0
	s_setprio 1
	v_mfma_f32_16x16x32_bf16 v[62:65], v[146:149], v[174:177], 0
	v_mfma_f32_16x16x32_bf16 v[62:65], v[150:153], v[178:181], v[62:65]
	v_mfma_f32_16x16x32_bf16 v[58:61], v[170:173], v[178:181], 0
	v_mfma_f32_16x16x32_bf16 v[58:61], v[154:157], v[174:177], v[58:61]
	v_mfma_f32_16x16x32_bf16 v[50:53], v[154:157], v[182:185], 0
	v_mfma_f32_16x16x32_bf16 v[50:53], v[170:173], v[186:189], v[50:53]
	v_mfma_f32_16x16x32_bf16 v[54:57], v[150:153], v[186:189], 0
	v_mfma_f32_16x16x32_bf16 v[54:57], v[146:149], v[182:185], v[54:57]
	v_mfma_f32_16x16x32_bf16 v[22:25], v[146:149], v[194:197], 0
	v_mfma_f32_16x16x32_bf16 v[22:25], v[150:153], v[198:201], v[22:25]
	v_mfma_f32_16x16x32_bf16 v[18:21], v[170:173], v[198:201], 0
	v_mfma_f32_16x16x32_bf16 v[18:21], v[154:157], v[194:197], v[18:21]
	v_mfma_f32_16x16x32_bf16 v[10:13], v[154:157], v[202:205], 0
	v_mfma_f32_16x16x32_bf16 v[10:13], v[170:173], v[206:209], v[10:13]
	v_mfma_f32_16x16x32_bf16 v[14:17], v[150:153], v[206:209], 0
	v_mfma_f32_16x16x32_bf16 v[14:17], v[146:149], v[202:205], v[14:17]
	s_setprio 0
	s_barrier
	s_branch .Lup_mid

; #define PG8_STAGE(bufoff, gbase, voff) do { _Pragma("unroll") for (int _i = 0; _i < 2; ++_i) \
;         __builtin_amdgcn_global_load_lds((const unsigned*)((const char*)(gbase) + (voff)[_i]), (PG8_LAS unsigned*)(lds + (bufoff) + ldsw + _i * 8192), 16, 0, 0); } while (0)
; #define PG8_LDA(dst, b, h) do { _Pragma("unroll") for (int m = 0; m < 4; ++m) _Pragma("unroll") for (int k = 0; k < 2; ++k) dst[m][k] = *(const PG8_LAS bf16x8*)(lds + PG8_SA(b, h) + aoff + m * 2048 + k * 1024); } while (0)
; #define PG8_LDB(dst, b, h) do { _Pragma("unroll") for (int n = 0; n < 2; ++n) _Pragma("unroll") for (int k = 0; k < 2; ++k) dst[n][k] = *(const PG8_LAS bf16x8*)(lds + PG8_SB(b, h) + boff + n * 2048 + k * 1024); } while (0)
; #define PG8_MMA(ai, bj, At, Bt) do { __builtin_amdgcn_s_setprio(1); _Pragma("unroll") for (int m = 0; m < 4; ++m) _Pragma("unroll") for (int n = 0; n < 2; ++n) _Pragma("unroll") for (int k = 0; k < 2; ++k) \
;         acc[ai][bj][m][n] = __builtin_amdgcn_mfma_f32_16x16x32_bf16(Bt[n][k], At[m][k], acc[ai][bj][m][n], 0, 0, 0); __builtin_amdgcn_s_setprio(0); } while (0)
; #define PG8_WAIT_V(n) asm volatile("s_waitcnt vmcnt(" #n ")" ::: "memory")
; #define PG8_WAIT_L(n) asm volatile("s_waitcnt lgkmcnt(" #n ")" ::: "memory")
; #define PG8_BAR __builtin_amdgcn_s_barrier()
; #define PG8_SCHED __builtin_amdgcn_sched_barrier(0)
;     ...
;             PG8_LDB(B0, 1, 0); PG8_LDB(B1, 1, 1); PG8_SCHED; PG8_LDA(At, 1, 0); PG8_STAGE(PG8_SA(0, 1), a2 + hstepA, voffA);
;             PG8_WAIT_V(8); PG8_WAIT_L(0); PG8_BAR; PG8_MMA(0, 0, At, B0); PG8_MMA(0, 1, At, B1); PG8_BAR; PG8_SCHED;
;             PG8_LDA(At, 1, 1); PG8_STAGE(PG8_SB(1, 0), b3, voffB); PG8_STAGE(PG8_SB(1, 1), b3 + hstepB, voffB); PG8_STAGE(PG8_SA(1, 0), a3, voffA);
;             PG8_WAIT_V(8); PG8_WAIT_L(0); PG8_BAR; PG8_MMA(1, 0, At, B0); PG8_MMA(1, 1, At, B1); PG8_BAR; PG8_SCHED;
.Lup_mid:
	s_add_i32 s88, 0, 0x18000
	v_add_u32_e32 v0, s88, v192
	s_add_i32 s89, 0, 0x1c000
	ds_read_b128 v[130:133], v0
	ds_read_b128 v[134:137], v0 offset:1024
	ds_read_b128 v[138:141], v0 offset:2048
	ds_read_b128 v[142:145], v0 offset:3072
	v_add_u32_e32 v0, s89, v192
	ds_read_b128 v[146:149], v0
	ds_read_b128 v[150:153], v0 offset:1024
	ds_read_b128 v[154:157], v0 offset:2048
	ds_read_b128 v[170:173], v0 offset:3072
	s_mov_b32 m0, s51
	v_lshl_add_u64 v[190:191], v[190:191], 0, s[58:59]
	ds_read_b128 v[174:177], v193 offset:32768
	ds_read_b128 v[178:181], v193 offset:33792
	ds_read_b128 v[182:185], v193 offset:34816
	ds_read_b128 v[186:189], v193 offset:35840
	ds_read_b128 v[194:197], v193 offset:36864
	ds_read_b128 v[198:201], v193 offset:37888
	ds_read_b128 v[202:205], v193 offset:38912
	ds_read_b128 v[206:209], v193 offset:39936
	global_load_lds_dwordx4 v[190:191], off
	v_lshl_add_u64 v[190:191], v[210:211], 0, s[58:59]
	s_mov_b32 m0, s54
	s_nop 0
	global_load_lds_dwordx4 v[190:191], off
	s_waitcnt vmcnt(8)
	s_waitcnt lgkmcnt(0)
	s_barrier
	s_setprio 1
	s_waitcnt lgkmcnt(0)
	v_mfma_f32_16x16x32_bf16 v[126:129], v[130:133], v[174:177], v[126:129]
	v_mfma_f32_16x16x32_bf16 v[126:129], v[134:137], v[178:181], v[126:129]
	v_mfma_f32_16x16x32_bf16 v[122:125], v[142:145], v[178:181], v[122:125]
	v_mfma_f32_16x16x32_bf16 v[122:125], v[138:141], v[174:177], v[122:125]
	v_mfma_f32_16x16x32_bf16 v[114:117], v[138:141], v[182:185], v[114:117]
	v_mfma_f32_16x16x32_bf16 v[114:117], v[142:145], v[186:189], v[114:117]
	v_mfma_f32_16x16x32_bf16 v[118:121], v[134:137], v[186:189], v[118:121]
	v_mfma_f32_16x16x32_bf16 v[118:121], v[130:133], v[182:185], v[118:121]
	v_mfma_f32_16x16x32_bf16 v[110:113], v[130:133], v[194:197], v[110:113]
	v_mfma_f32_16x16x32_bf16 v[110:113], v[134:137], v[198:201], v[110:113]
	v_mfma_f32_16x16x32_bf16 v[106:109], v[142:145], v[198:201], v[106:109]
	v_mfma_f32_16x16x32_bf16 v[106:109], v[138:141], v[194:197], v[106:109]
	v_mfma_f32_16x16x32_bf16 v[98:101], v[138:141], v[202:205], v[98:101]
	v_mfma_f32_16x16x32_bf16 v[98:101], v[142:145], v[206:209], v[98:101]
	v_mfma_f32_16x16x32_bf16 v[102:105], v[134:137], v[206:209], v[102:105]
	v_mfma_f32_16x16x32_bf16 v[102:105], v[130:133], v[202:205], v[102:105]
	s_setprio 0
	s_setprio 1
	v_mfma_f32_16x16x32_bf16 v[30:33], v[146:149], v[174:177], v[30:33]
	v_mfma_f32_16x16x32_bf16 v[30:33], v[150:153], v[178:181], v[30:33]
	v_mfma_f32_16x16x32_bf16 v[46:49], v[170:173], v[178:181], v[46:49]
	v_mfma_f32_16x16x32_bf16 v[46:49], v[154:157], v[174:177], v[46:49]
	v_mfma_f32_16x16x32_bf16 v[34:37], v[154:157], v[182:185], v[34:37]
	v_mfma_f32_16x16x32_bf16 v[34:37], v[170:173], v[186:189], v[34:37]
	v_mfma_f32_16x16x32_bf16 v[26:29], v[150:153], v[186:189], v[26:29]
	v_mfma_f32_16x16x32_bf16 v[26:29], v[146:149], v[182:185], v[26:29]
	v_mfma_f32_16x16x32_bf16 v[94:97], v[146:149], v[194:197], v[94:97]
	v_mfma_f32_16x16x32_bf16 v[94:97], v[150:153], v[198:201], v[94:97]
	v_mfma_f32_16x16x32_bf16 v[90:93], v[170:173], v[198:201], v[90:93]
	v_mfma_f32_16x16x32_bf16 v[90:93], v[154:157], v[194:197], v[90:93]
	v_mfma_f32_16x16x32_bf16 v[82:85], v[154:157], v[202:205], v[82:85]
	v_mfma_f32_16x16x32_bf16 v[82:85], v[170:173], v[206:209], v[82:85]
	v_mfma_f32_16x16x32_bf16 v[86:89], v[150:153], v[206:209], v[86:89]
	v_mfma_f32_16x16x32_bf16 v[86:89], v[146:149], v[202:205], v[86:89]
	s_setprio 0
	s_barrier
	s_add_u32 s34, s86, 0x8000
	s_addc_u32 s35, s87, 0
	s_add_i32 s88, s88, s44
	s_mov_b32 m0, s88
	ds_read_b128 v[174:177], v193 offset:49152
	ds_read_b128 v[178:181], v193 offset:50176
	ds_read_b128 v[182:185], v193 offset:51200
	ds_read_b128 v[186:189], v193 offset:52224
	ds_read_b128 v[194:197], v193 offset:53248
	ds_read_b128 v[198:201], v193 offset:54272
	ds_read_b128 v[202:205], v193 offset:55296
	ds_read_b128 v[206:209], v193 offset:56320
	global_load_lds_dwordx4 v162, s[34:35]
	s_add_i32 m0, s88, 0x2000
	v_lshl_add_u64 v[190:191], s[34:35], 0, v[158:159]
	s_add_u32 s34, s86, 0xc000
	s_addc_u32 s35, s87, 0
	s_add_i32 s86, s89, s44
	global_load_lds_dwordx4 v[190:191], off
	s_mov_b32 m0, s86
	s_nop 0
	global_load_lds_dwordx4 v162, s[34:35]
	s_add_i32 m0, s86, 0x2000
	s_nop 0
	global_load_lds_dwordx4 v158, s[34:35]
	s_mov_b32 m0, s85
	s_nop 0
	global_load_lds_dwordx4 v164, s[46:47]
	v_lshl_add_u64 v[190:191], s[46:47], 0, v[160:161]
	s_mov_b32 m0, s90
	s_nop 0
	global_load_lds_dwordx4 v[190:191], off
	s_waitcnt vmcnt(8)
	s_waitcnt lgkmcnt(0)
	s_barrier
	s_setprio 1
	s_waitcnt lgkmcnt(0)
	v_mfma_f32_16x16x32_bf16 v[78:81], v[130:133], v[174:177], v[78:81]
	v_mfma_f32_16x16x32_bf16 v[78:81], v[134:137], v[178:181], v[78:81]
	v_mfma_f32_16x16x32_bf16 v[74:77], v[142:145], v[178:181], v[74:77]
	v_mfma_f32_16x16x32_bf16 v[74:77], v[138:141], v[174:177], v[74:77]
	v_mfma_f32_16x16x32_bf16 v[66:69], v[138:141], v[182:185], v[66:69]
	v_mfma_f32_16x16x32_bf16 v[66:69], v[142:145], v[186:189], v[66:69]
	v_mfma_f32_16x16x32_bf16 v[70:73], v[134:137], v[186:189], v[70:73]
	v_mfma_f32_16x16x32_bf16 v[70:73], v[130:133], v[182:185], v[70:73]
	v_mfma_f32_16x16x32_bf16 v[42:45], v[130:133], v[194:197], v[42:45]
	v_mfma_f32_16x16x32_bf16 v[42:45], v[134:137], v[198:201], v[42:45]
	v_mfma_f32_16x16x32_bf16 v[6:9], v[142:145], v[198:201], v[6:9]
	v_mfma_f32_16x16x32_bf16 v[6:9], v[138:141], v[194:197], v[6:9]
	v_mfma_f32_16x16x32_bf16 v[2:5], v[138:141], v[202:205], v[2:5]
	v_mfma_f32_16x16x32_bf16 v[2:5], v[142:145], v[206:209], v[2:5]
	v_mfma_f32_16x16x32_bf16 v[38:41], v[134:137], v[206:209], v[38:41]
	v_mfma_f32_16x16x32_bf16 v[38:41], v[130:133], v[202:205], v[38:41]
	s_setprio 0
	s_setprio 1
	v_mfma_f32_16x16x32_bf16 v[62:65], v[146:149], v[174:177], v[62:65]
	v_mfma_f32_16x16x32_bf16 v[62:65], v[150:153], v[178:181], v[62:65]
	v_mfma_f32_16x16x32_bf16 v[58:61], v[170:173], v[178:181], v[58:61]
	v_mfma_f32_16x16x32_bf16 v[58:61], v[154:157], v[174:177], v[58:61]
	v_mfma_f32_16x16x32_bf16 v[50:53], v[154:157], v[182:185], v[50:53]
	v_mfma_f32_16x16x32_bf16 v[50:53], v[170:173], v[186:189], v[50:53]
	v_mfma_f32_16x16x32_bf16 v[54:57], v[150:153], v[186:189], v[54:57]
	v_mfma_f32_16x16x32_bf16 v[54:57], v[146:149], v[182:185], v[54:57]
	v_mfma_f32_16x16x32_bf16 v[22:25], v[146:149], v[194:197], v[22:25]
	v_mfma_f32_16x16x32_bf16 v[22:25], v[150:153], v[198:201], v[22:25]
	v_mfma_f32_16x16x32_bf16 v[18:21], v[170:173], v[198:201], v[18:21]
	v_mfma_f32_16x16x32_bf16 v[18:21], v[154:157], v[194:197], v[18:21]
	v_mfma_f32_16x16x32_bf16 v[10:13], v[154:157], v[202:205], v[10:13]
	v_mfma_f32_16x16x32_bf16 v[10:13], v[170:173], v[206:209], v[10:13]
	v_mfma_f32_16x16x32_bf16 v[14:17], v[150:153], v[206:209], v[14:17]
	v_mfma_f32_16x16x32_bf16 v[14:17], v[146:149], v[202:205], v[14:17]
	s_setprio 0
	s_barrier
	s_add_i32 s66, s66, 2
	s_add_u32 vcc_hi, vcc_hi, 0x10000
	s_addc_u32 s65, s65, 0
	s_cmp_gt_u32 s66, 29
	s_mov_b64 s[34:35], s[36:37]
	s_cbranch_scc0 .LBB0_1256
	s_and_b64 vcc, exec, s[18:19]
	s_cbranch_vccz .LBB0_1259
	s_barrier

; __device__ __forceinline__ void store_wt(void* p, const u32x4 v) { asm volatile("global_store_dwordx4 %0, %1, off sc1\n\ts_nop 2" :: "v"(p), "v"(v) : "memory"); }
;     __device__ __forceinline__ void operator()(f32x4 (&acc)[2][2][4][2], const pg8::Unit& u, int ui, int wr, int wc, int fr, int fq) const {
;     ...
;         {   f32x4 swa[2], swv[2];
; #pragma unroll
;             for (int n = 0; n < 2; ++n) { swa[n] = *(const f32x4*)(SW + (size_t)b * NUP + swc + n * 4); swv[n] = *(const f32x4*)(SW + (size_t)b * NUP + swc + 128 + n * 4); }
; #pragma unroll
;             for (int ai = 0; ai < 2; ++ai)
; #pragma unroll
;                 for (int m = 0; m < 4; ++m) { const float r = RSTD[ui * 256 + lrow + 4 * ai + m];
; #pragma unroll
;                     for (int n = 0; n < 2; ++n) { acc[ai][0][m][n] = acc[ai][0][m][n] * r + swa[n]; acc[ai][1][m][n] = acc[ai][1][m][n] * r + swv[n]; } }
;         }
;         {   const int kb = u.pm * 2 + wr;
;             if (fr == 0) { float* pa = HA + ((size_t)kb * 4) * DFF + jc; float* pv = HV + ((size_t)kb * 2) * DFF + jc;
;                 *(f32x4*)pa = acc[0][0][0][0]; *(f32x4*)(pa + 4) = acc[0][0][0][1]; *(f32x4*)(pa + DFF) = acc[0][0][1][0]; *(f32x4*)(pa + DFF + 4) = acc[0][0][1][1];
;                 *(f32x4*)pv = acc[0][1][0][0]; *(f32x4*)(pv + 4) = acc[0][1][0][1]; *(f32x4*)(pv + DFF) = acc[0][1][1][0]; *(f32x4*)(pv + DFF + 4) = acc[0][1][1][1]; }
;             if (fr == 15) { float* pa = HA + ((size_t)kb * 4 + 2) * DFF + jc;
;                 store_wt(pa, __builtin_bit_cast(u32x4, acc[1][0][2][0])); store_wt(pa + 4, __builtin_bit_cast(u32x4, acc[1][0][2][1])); store_wt(pa + DFF, __builtin_bit_cast(u32x4, acc[1][0][3][0])); store_wt(pa + DFF + 4, __builtin_bit_cast(u32x4, acc[1][0][3][1])); } }
; #pragma unroll
;         for (int n = 0; n < 2; ++n) {
;             const f32x4 cbv = *(const f32x4*)(cb + jc + n * 4), w0 = *(const f32x4*)(cw + jc + n * 4), w1 = *(const f32x4*)(cw + DFF + jc + n * 4), w2 = *(const f32x4*)(cw + 2 * DFF + jc + n * 4);
;             f32x4 p2, p1;
;             { const f32x4 x6 = acc[1][0][2][n], x7 = acc[1][0][3][n];
;               p2 = (f32x4){dpp_z<0x111>(x6.x), dpp_z<0x111>(x6.y), dpp_z<0x111>(x6.z), dpp_z<0x111>(x6.w)};
;               p1 = (f32x4){dpp_z<0x111>(x7.x), dpp_z<0x111>(x7.y), dpp_z<0x111>(x7.z), dpp_z<0x111>(x7.w)}; }
.LBB0_1265:
	s_or_b64 exec, exec, s[34:35]
	v_mov_b32_e32 v194, v148
	v_mov_b32_e32 v195, v148
	v_pk_fma_f32 v[116:117], v[94:95], v[156:157], v[138:139] op_sel_hi:[1,0,1]
	v_pk_fma_f32 v[94:95], v[108:109], v[156:157], v[144:145] op_sel_hi:[1,0,1]
	v_pk_fma_f32 v[108:109], v[90:91], v[156:157], v[134:135] op_sel_hi:[1,0,1]
	v_mov_b32_e32 v90, v157
	v_mov_b32_e32 v196, v149
	v_mov_b32_e32 v197, v149
	v_pk_fma_f32 v[184:185], v[112:113], v[156:157], v[152:153] op_sel_hi:[1,0,1]
	v_pk_fma_f32 v[186:187], v[110:111], v[156:157], v[150:151] op_sel_hi:[1,0,1]
	v_pk_fma_f32 v[114:115], v[96:97], v[156:157], v[140:141] op_sel_hi:[1,0,1]
	v_pk_fma_f32 v[96:97], v[106:107], v[156:157], v[142:143] op_sel_hi:[1,0,1]
	v_pk_fma_f32 v[106:107], v[92:93], v[156:157], v[136:137] op_sel_hi:[1,0,1]
	v_pk_fma_f32 v[190:191], v[86:87], v[90:91], v[138:139] op_sel_hi:[1,0,1]
	v_pk_fma_f32 v[86:87], v[100:101], v[90:91], v[144:145] op_sel_hi:[1,0,1]
	v_pk_fma_f32 v[100:101], v[82:83], v[90:91], v[134:135] op_sel_hi:[1,0,1]
	v_pk_fma_f32 v[156:157], v[80:81], v[146:147], v[152:153] op_sel_hi:[1,0,1]
	v_pk_fma_f32 v[80:81], v[76:77], v[146:147], v[144:145] op_sel_hi:[1,0,1]
	v_pk_fma_f32 v[82:83], v[50:51], v[146:147], v[134:135] op_sel:[0,1,0]
	v_mov_b32_e32 v50, v148
	v_mov_b32_e32 v51, v148
	v_pk_fma_f32 v[76:77], v[18:19], v[194:195], v[134:135]
	v_lshlrev_b64 v[18:19], 2, v[170:171]
	v_pk_fma_f32 v[176:177], v[104:105], v[90:91], v[152:153] op_sel_hi:[1,0,1]
	v_pk_fma_f32 v[154:155], v[78:79], v[146:147], v[150:151] op_sel_hi:[1,0,1]
	v_pk_fma_f32 v[180:181], v[62:63], v[146:147], v[138:139] op_sel_hi:[1,0,1]
	v_pk_fma_f32 v[78:79], v[74:75], v[146:147], v[142:143] op_sel_hi:[1,0,1]
	v_pk_fma_f32 v[152:153], v[72:73], v[146:147], v[152:153] op_sel:[0,1,0]
	v_pk_fma_f32 v[172:173], v[54:55], v[146:147], v[138:139] op_sel:[0,1,0]
	v_pk_fma_f32 v[72:73], v[68:69], v[146:147], v[144:145] op_sel:[0,1,0]
	v_pk_fma_f32 v[144:145], v[22:23], v[194:195], v[138:139]
	v_pk_fma_f32 v[74:75], v[20:21], v[50:51], v[136:137]
	v_mov_b32_e32 v148, v149
	v_pk_fma_f32 v[138:139], v[14:15], v[196:197], v[138:139]
	v_lshl_add_u64 v[14:15], s[16:17], 0, v[18:19]
	v_lshl_add_u64 v[20:21], s[14:15], 0, v[18:19]
	v_pk_fma_f32 v[178:179], v[102:103], v[90:91], v[150:151] op_sel_hi:[1,0,1]
	v_pk_fma_f32 v[188:189], v[88:89], v[90:91], v[140:141] op_sel_hi:[1,0,1]
	v_pk_fma_f32 v[88:89], v[98:99], v[90:91], v[142:143] op_sel_hi:[1,0,1]
	v_pk_fma_f32 v[98:99], v[84:85], v[90:91], v[136:137] op_sel_hi:[1,0,1]
	v_pk_fma_f32 v[182:183], v[64:65], v[146:147], v[140:141] op_sel_hi:[1,0,1]
	v_pk_fma_f32 v[150:151], v[70:71], v[146:147], v[150:151] op_sel:[0,1,0]
	v_pk_fma_f32 v[174:175], v[56:57], v[146:147], v[140:141] op_sel:[0,1,0]
	v_pk_fma_f32 v[70:71], v[66:67], v[146:147], v[142:143] op_sel:[0,1,0]
	v_pk_fma_f32 v[84:85], v[52:53], v[146:147], v[136:137] op_sel:[0,1,0]
	v_pk_fma_f32 v[142:143], v[24:25], v[50:51], v[140:141]
	v_pk_fma_f32 v[140:141], v[16:17], v[148:149], v[140:141]
	v_pk_fma_f32 v[66:67], v[12:13], v[148:149], v[136:137]
	v_pk_fma_f32 v[68:69], v[10:11], v[196:197], v[134:135]
	global_load_dwordx4 v[10:13], v[14:15], off offset:16
	global_load_dwordx4 v[50:53], v[14:15], off
	s_nop 0
	global_load_dwordx4 v[14:17], v[20:21], off offset:16
	global_load_dwordx4 v[54:57], v[20:21], off
	v_lshl_add_u64 v[20:21], s[20:21], 0, v[18:19]
	v_pk_fma_f32 v[90:91], v[58:59], v[146:147], v[134:135] op_sel_hi:[1,0,1]
	global_load_dwordx4 v[22:25], v[20:21], off offset:16
	global_load_dwordx4 v[62:65], v[20:21], off
	v_lshl_add_u64 v[58:59], s[22:23], 0, v[18:19]
	v_pk_fma_f32 v[92:93], v[60:61], v[146:147], v[136:137] op_sel_hi:[1,0,1]
	global_load_dwordx4 v[18:21], v[58:59], off offset:16
	s_nop 0
	global_load_dwordx4 v[58:61], v[58:59], off
	v_mov_b32_e32 v102, 0
	v_mov_b32_e32 v103, 0
	v_mov_b32_e32 v104, 0
	v_mov_b32_e32 v105, 0
	v_mov_b32_dpp v102, v42 row_shr:1 row_mask:0xf bank_mask:0xf
	v_mov_b32_dpp v103, v43 row_shr:1 row_mask:0xf bank_mask:0xf
	v_mov_b32_dpp v104, v44 row_shr:1 row_mask:0xf bank_mask:0xf
	v_mov_b32_dpp v105, v45 row_shr:1 row_mask:0xf bank_mask:0xf
	v_mov_b32_e32 v110, 0
	v_mov_b32_e32 v111, 0
	v_mov_b32_e32 v112, 0
	v_mov_b32_e32 v113, 0
	v_mov_b32_dpp v110, v38 row_shr:1 row_mask:0xf bank_mask:0xf
	v_mov_b32_dpp v111, v39 row_shr:1 row_mask:0xf bank_mask:0xf
	v_mov_b32_dpp v112, v40 row_shr:1 row_mask:0xf bank_mask:0xf
	v_mov_b32_dpp v113, v41 row_shr:1 row_mask:0xf bank_mask:0xf
	s_mul_hi_i32 s11, s10, 0x2c0000
	s_mul_i32 s10, s10, 0x2c0000
	s_add_u32 s10, s67, s10
	s_addc_u32 s11, s68, s11
	s_andn2_b64 vcc, exec, s[6:7]
	s_waitcnt vmcnt(4)
	v_pk_fma_f32 v[104:105], v[56:57], v[104:105], v[52:53]
	v_pk_fma_f32 v[102:103], v[54:55], v[102:103], v[50:51]
	s_waitcnt vmcnt(2)
	v_pk_fma_f32 v[104:105], v[64:65], v[112:113], v[104:105]
	v_pk_fma_f32 v[102:103], v[62:63], v[110:111], v[102:103]
	v_pk_fma_f32 v[112:113], v[56:57], v[112:113], v[52:53]
	s_waitcnt vmcnt(0)
; __device__ __forceinline__ f32x4 silu4(const f32x4 p) { f32x4 r; r.x = siluf(p.x); r.y = siluf(p.y); r.z = siluf(p.z); r.w = siluf(p.w); return r; }
;     __device__ __forceinline__ void operator()(f32x4 (&acc)[2][2][4][2], const pg8::Unit& u, int ui, int wr, int wc, int fr, int fq) const {
;     ...
; #pragma unroll
;             for (int j = 0; j < 8; ++j) { const f32x4 x = acc[j >> 2][0][j & 3][n];
;                 const f32x4 cv = cbv + w0 * p2 + w1 * p1 + w2 * x;
;                 acc[j >> 2][1][j & 3][n] = silu4(cv) * acc[j >> 2][1][j & 3][n];
;                 p2 = p1; p1 = x; }
	v_pk_fma_f32 v[104:105], v[128:129], v[60:61], v[104:105]
	v_pk_fma_f32 v[102:103], v[126:127], v[58:59], v[102:103]
	v_mul_f32_e32 v136, 0xbfb8aa3b, v104
	v_mul_f32_e32 v134, 0xbfb8aa3b, v102
	v_mul_f32_e32 v135, 0xbfb8aa3b, v103
	v_mul_f32_e32 v137, 0xbfb8aa3b, v105
	v_exp_f32_e32 v134, v134
	v_exp_f32_e32 v135, v135
	v_exp_f32_e32 v136, v136
	v_exp_f32_e32 v137, v137
	v_add_f32_e32 v134, 1.0, v134
	v_add_f32_e32 v135, 1.0, v135
	v_add_f32_e32 v136, 1.0, v136
	v_add_f32_e32 v137, 1.0, v137
	v_rcp_f32_e32 v134, v134
	v_rcp_f32_e32 v135, v135
	v_rcp_f32_e32 v136, v136
	v_rcp_f32_e32 v137, v137
	v_pk_fma_f32 v[110:111], v[54:55], v[110:111], v[50:51]
	v_pk_fma_f32 v[112:113], v[128:129], v[64:65], v[112:113]
	v_pk_fma_f32 v[110:111], v[126:127], v[62:63], v[110:111]
	v_pk_mul_f32 v[104:105], v[104:105], v[136:137]
	v_pk_mul_f32 v[134:135], v[102:103], v[134:135]
	v_pk_fma_f32 v[112:113], v[120:121], v[60:61], v[112:113]
	v_pk_fma_f32 v[110:111], v[118:119], v[58:59], v[110:111]
	v_pk_mul_f32 v[102:103], v[132:133], v[104:105]
	v_pk_mul_f32 v[104:105], v[130:131], v[134:135]
	v_mul_f32_e32 v130, 0xbfb8aa3b, v110
	v_mul_f32_e32 v131, 0xbfb8aa3b, v111
	v_mul_f32_e32 v132, 0xbfb8aa3b, v112
	v_mul_f32_e32 v133, 0xbfb8aa3b, v113
	v_exp_f32_e32 v130, v130
	v_exp_f32_e32 v131, v131
	v_exp_f32_e32 v132, v132
	v_exp_f32_e32 v133, v133
	v_add_f32_e32 v130, 1.0, v130
	v_add_f32_e32 v131, 1.0, v131
	v_add_f32_e32 v132, 1.0, v132
	v_add_f32_e32 v133, 1.0, v133
	v_rcp_f32_e32 v130, v130
	v_rcp_f32_e32 v131, v131
	v_rcp_f32_e32 v132, v132
	v_rcp_f32_e32 v133, v133
	v_pk_mul_f32 v[130:131], v[110:111], v[130:131]
	v_pk_mul_f32 v[112:113], v[112:113], v[132:133]
	s_nop 0
	v_pk_mul_f32 v[110:111], v[124:125], v[112:113]
	v_pk_mul_f32 v[112:113], v[122:123], v[130:131]
	v_pk_fma_f32 v[122:123], v[128:129], v[56:57], v[52:53]
	v_pk_fma_f32 v[124:125], v[126:127], v[54:55], v[50:51]
	v_pk_fma_f32 v[122:123], v[120:121], v[64:65], v[122:123]
	v_pk_fma_f32 v[124:125], v[118:119], v[62:63], v[124:125]
	v_pk_fma_f32 v[122:123], v[184:185], v[60:61], v[122:123]
	v_pk_fma_f32 v[124:125], v[186:187], v[58:59], v[124:125]
	v_mul_f32_e32 v128, 0xbfb8aa3b, v122
	v_mul_f32_e32 v126, 0xbfb8aa3b, v124
	v_mul_f32_e32 v127, 0xbfb8aa3b, v125
	v_mul_f32_e32 v129, 0xbfb8aa3b, v123
	v_exp_f32_e32 v126, v126
	v_exp_f32_e32 v127, v127
	v_exp_f32_e32 v128, v128
	v_exp_f32_e32 v129, v129
	v_add_f32_e32 v126, 1.0, v126
	v_add_f32_e32 v127, 1.0, v127
	v_add_f32_e32 v128, 1.0, v128
	v_add_f32_e32 v129, 1.0, v129
	v_rcp_f32_e32 v126, v126
	v_rcp_f32_e32 v127, v127
	v_rcp_f32_e32 v128, v128
	v_rcp_f32_e32 v129, v129
	v_pk_fma_f32 v[120:121], v[120:121], v[56:57], v[52:53]
	v_pk_fma_f32 v[118:119], v[118:119], v[54:55], v[50:51]
	v_pk_fma_f32 v[120:121], v[184:185], v[64:65], v[120:121]
	v_pk_fma_f32 v[118:119], v[186:187], v[62:63], v[118:119]
	v_pk_mul_f32 v[122:123], v[122:123], v[128:129]
	v_pk_mul_f32 v[124:125], v[124:125], v[126:127]
	v_pk_fma_f32 v[120:121], v[176:177], v[60:61], v[120:121]
	v_pk_fma_f32 v[118:119], v[178:179], v[58:59], v[118:119]
	v_pk_mul_f32 v[114:115], v[114:115], v[122:123]
	v_pk_mul_f32 v[116:117], v[116:117], v[124:125]
	v_mul_f32_e32 v122, 0xbfb8aa3b, v118
	v_mul_f32_e32 v123, 0xbfb8aa3b, v119
	v_mul_f32_e32 v124, 0xbfb8aa3b, v120
	v_mul_f32_e32 v125, 0xbfb8aa3b, v121
	v_exp_f32_e32 v122, v122
	v_exp_f32_e32 v123, v123
	v_exp_f32_e32 v124, v124
	v_exp_f32_e32 v125, v125
	v_add_f32_e32 v122, 1.0, v122
	v_add_f32_e32 v123, 1.0, v123
	v_add_f32_e32 v124, 1.0, v124
	v_add_f32_e32 v125, 1.0, v125
	v_rcp_f32_e32 v122, v122
	v_rcp_f32_e32 v123, v123
	v_rcp_f32_e32 v124, v124
	v_rcp_f32_e32 v125, v125
	v_pk_mul_f32 v[122:123], v[118:119], v[122:123]
	v_pk_mul_f32 v[120:121], v[120:121], v[124:125]
	s_nop 0
	v_pk_mul_f32 v[118:119], v[188:189], v[120:121]
	v_pk_mul_f32 v[120:121], v[190:191], v[122:123]
	v_pk_fma_f32 v[122:123], v[186:187], v[54:55], v[50:51]
	v_pk_fma_f32 v[124:125], v[184:185], v[56:57], v[52:53]
	v_pk_fma_f32 v[122:123], v[178:179], v[62:63], v[122:123]
	v_pk_fma_f32 v[124:125], v[176:177], v[64:65], v[124:125]
	v_pk_fma_f32 v[122:123], v[154:155], v[58:59], v[122:123]
	v_pk_fma_f32 v[124:125], v[156:157], v[60:61], v[124:125]
	v_mul_f32_e32 v126, 0xbfb8aa3b, v122
	v_mul_f32_e32 v127, 0xbfb8aa3b, v123
	v_mul_f32_e32 v128, 0xbfb8aa3b, v124
	v_mul_f32_e32 v129, 0xbfb8aa3b, v125
	v_exp_f32_e32 v126, v126
	v_exp_f32_e32 v127, v127
	v_exp_f32_e32 v128, v128
	v_exp_f32_e32 v129, v129
	v_add_f32_e32 v126, 1.0, v126
	v_add_f32_e32 v127, 1.0, v127
	v_add_f32_e32 v128, 1.0, v128
	v_add_f32_e32 v129, 1.0, v129
	v_rcp_f32_e32 v126, v126
	v_rcp_f32_e32 v127, v127
	v_rcp_f32_e32 v128, v128
	v_rcp_f32_e32 v129, v129
	v_pk_mul_f32 v[126:127], v[122:123], v[126:127]
	v_pk_mul_f32 v[124:125], v[124:125], v[128:129]
	s_nop 0
	v_pk_mul_f32 v[122:123], v[182:183], v[124:125]
	v_pk_mul_f32 v[124:125], v[180:181], v[126:127]
	v_pk_fma_f32 v[126:127], v[176:177], v[56:57], v[52:53]
	v_pk_fma_f32 v[128:129], v[178:179], v[54:55], v[50:51]
	v_pk_fma_f32 v[126:127], v[156:157], v[64:65], v[126:127]
	v_pk_fma_f32 v[128:129], v[154:155], v[62:63], v[128:129]
	v_pk_fma_f32 v[126:127], v[152:153], v[60:61], v[126:127]
	v_pk_fma_f32 v[128:129], v[150:151], v[58:59], v[128:129]
	v_mul_f32_e32 v132, 0xbfb8aa3b, v126
	v_mul_f32_e32 v130, 0xbfb8aa3b, v128
	v_mul_f32_e32 v131, 0xbfb8aa3b, v129
	v_mul_f32_e32 v133, 0xbfb8aa3b, v127
	v_exp_f32_e32 v130, v130
	v_exp_f32_e32 v131, v131
	v_exp_f32_e32 v132, v132
	v_exp_f32_e32 v133, v133
	v_add_f32_e32 v130, 1.0, v130
	v_add_f32_e32 v131, 1.0, v131
	v_add_f32_e32 v132, 1.0, v132
	v_add_f32_e32 v133, 1.0, v133
	v_rcp_f32_e32 v130, v130
; __device__ __forceinline__ f32x4 silu4(const f32x4 p) { f32x4 r; r.x = siluf(p.x); r.y = siluf(p.y); r.z = siluf(p.z); r.w = siluf(p.w); return r; }
; template <int CTRL> __device__ __forceinline__ float dpp_z(float v) { return __int_as_float(__builtin_amdgcn_update_dpp(0, __float_as_int(v), CTRL, 0xf, 0xf, false)); }
;     __device__ __forceinline__ void operator()(f32x4 (&acc)[2][2][4][2], const pg8::Unit& u, int ui, int wr, int wc, int fr, int fq) const {
;     ...
;         for (int n = 0; n < 2; ++n) {
;             const f32x4 cbv = *(const f32x4*)(cb + jc + n * 4), w0 = *(const f32x4*)(cw + jc + n * 4), w1 = *(const f32x4*)(cw + DFF + jc + n * 4), w2 = *(const f32x4*)(cw + 2 * DFF + jc + n * 4);
;             f32x4 p2, p1;
;             { const f32x4 x6 = acc[1][0][2][n], x7 = acc[1][0][3][n];
;               p2 = (f32x4){dpp_z<0x111>(x6.x), dpp_z<0x111>(x6.y), dpp_z<0x111>(x6.z), dpp_z<0x111>(x6.w)};
;               p1 = (f32x4){dpp_z<0x111>(x7.x), dpp_z<0x111>(x7.y), dpp_z<0x111>(x7.z), dpp_z<0x111>(x7.w)}; }
; #pragma unroll
;             for (int j = 0; j < 8; ++j) { const f32x4 x = acc[j >> 2][0][j & 3][n];
;                 const f32x4 cv = cbv + w0 * p2 + w1 * p1 + w2 * x;
;                 acc[j >> 2][1][j & 3][n] = silu4(cv) * acc[j >> 2][1][j & 3][n];
;                 p2 = p1; p1 = x; }
	v_rcp_f32_e32 v131, v131
	v_rcp_f32_e32 v132, v132
	v_rcp_f32_e32 v133, v133
	v_pk_mul_f32 v[128:129], v[128:129], v[130:131]
	v_pk_fma_f32 v[130:131], v[156:157], v[56:57], v[52:53]
	v_pk_mul_f32 v[126:127], v[126:127], v[132:133]
	v_pk_fma_f32 v[132:133], v[154:155], v[54:55], v[50:51]
	v_pk_fma_f32 v[130:131], v[152:153], v[64:65], v[130:131]
	v_pk_fma_f32 v[132:133], v[150:151], v[62:63], v[132:133]
	v_pk_fma_f32 v[52:53], v[152:153], v[56:57], v[52:53]
	v_pk_fma_f32 v[50:51], v[150:151], v[54:55], v[50:51]
	v_pk_fma_f32 v[130:131], v[44:45], v[60:61], v[130:131]
	v_pk_fma_f32 v[132:133], v[42:43], v[58:59], v[132:133]
	v_pk_fma_f32 v[44:45], v[44:45], v[64:65], v[52:53]
	v_pk_fma_f32 v[42:43], v[42:43], v[62:63], v[50:51]
	v_pk_fma_f32 v[40:41], v[40:41], v[60:61], v[44:45]
	v_pk_fma_f32 v[38:39], v[38:39], v[58:59], v[42:43]
	v_mul_f32_e32 v44, 0xbfb8aa3b, v40
	v_mul_f32_e32 v42, 0xbfb8aa3b, v38
	v_mul_f32_e32 v43, 0xbfb8aa3b, v39
	v_mul_f32_e32 v45, 0xbfb8aa3b, v41
	v_exp_f32_e32 v42, v42
	v_exp_f32_e32 v43, v43
	v_exp_f32_e32 v44, v44
	v_exp_f32_e32 v45, v45
	v_add_f32_e32 v42, 1.0, v42
	v_add_f32_e32 v43, 1.0, v43
	v_add_f32_e32 v44, 1.0, v44
	v_add_f32_e32 v45, 1.0, v45
	v_rcp_f32_e32 v42, v42
	v_rcp_f32_e32 v43, v43
	v_rcp_f32_e32 v44, v44
	v_rcp_f32_e32 v45, v45
	v_mov_b32_e32 v50, 0
	v_pk_mul_f32 v[42:43], v[38:39], v[42:43]
	v_mov_b32_e32 v51, 0
	v_pk_mul_f32 v[40:41], v[40:41], v[44:45]
	v_mov_b32_e32 v44, 0
	v_pk_mul_f32 v[38:39], v[140:141], v[40:41]
	v_pk_mul_f32 v[40:41], v[138:139], v[42:43]
	v_mov_b32_e32 v42, 0
	v_mov_b32_e32 v43, 0
	v_mov_b32_e32 v45, 0
	v_mov_b32_dpp v42, v6 row_shr:1 row_mask:0xf bank_mask:0xf
	v_mov_b32_dpp v43, v7 row_shr:1 row_mask:0xf bank_mask:0xf
	v_mov_b32_dpp v44, v8 row_shr:1 row_mask:0xf bank_mask:0xf
	v_mov_b32_dpp v45, v9 row_shr:1 row_mask:0xf bank_mask:0xf
	v_mov_b32_e32 v52, 0
	v_mov_b32_e32 v53, 0
	v_mov_b32_dpp v50, v2 row_shr:1 row_mask:0xf bank_mask:0xf
	v_mov_b32_dpp v51, v3 row_shr:1 row_mask:0xf bank_mask:0xf
	v_mov_b32_dpp v52, v4 row_shr:1 row_mask:0xf bank_mask:0xf
	v_mov_b32_dpp v53, v5 row_shr:1 row_mask:0xf bank_mask:0xf
	v_pk_fma_f32 v[44:45], v[16:17], v[44:45], v[12:13]
	v_pk_fma_f32 v[42:43], v[14:15], v[42:43], v[10:11]
	v_pk_fma_f32 v[44:45], v[24:25], v[52:53], v[44:45]
	v_pk_fma_f32 v[42:43], v[22:23], v[50:51], v[42:43]
	v_pk_fma_f32 v[44:45], v[32:33], v[20:21], v[44:45]
	v_pk_fma_f32 v[42:43], v[30:31], v[18:19], v[42:43]
	v_mul_f32_e32 v56, 0xbfb8aa3b, v44
	v_mul_f32_e32 v54, 0xbfb8aa3b, v42
	v_mul_f32_e32 v55, 0xbfb8aa3b, v43
	v_mul_f32_e32 v57, 0xbfb8aa3b, v45
	v_exp_f32_e32 v54, v54
	v_exp_f32_e32 v55, v55
	v_exp_f32_e32 v56, v56
	v_exp_f32_e32 v57, v57
	v_add_f32_e32 v54, 1.0, v54
	v_add_f32_e32 v55, 1.0, v55
	v_add_f32_e32 v56, 1.0, v56
	v_add_f32_e32 v57, 1.0, v57
	v_rcp_f32_e32 v54, v54
	v_rcp_f32_e32 v55, v55
	v_rcp_f32_e32 v56, v56
	v_rcp_f32_e32 v57, v57
	v_mul_f32_e32 v134, 0xbfb8aa3b, v132
	v_pk_mul_f32 v[54:55], v[42:43], v[54:55]
	v_mul_f32_e32 v135, 0xbfb8aa3b, v133
	v_pk_mul_f32 v[44:45], v[44:45], v[56:57]
	v_mul_f32_e32 v136, 0xbfb8aa3b, v130
	v_pk_mul_f32 v[42:43], v[48:49], v[44:45]
	v_pk_mul_f32 v[44:45], v[46:47], v[54:55]
	v_pk_fma_f32 v[46:47], v[16:17], v[52:53], v[12:13]
	v_pk_fma_f32 v[48:49], v[14:15], v[50:51], v[10:11]
	v_pk_fma_f32 v[46:47], v[32:33], v[24:25], v[46:47]
	v_pk_fma_f32 v[48:49], v[30:31], v[22:23], v[48:49]
	v_pk_fma_f32 v[46:47], v[28:29], v[20:21], v[46:47]
	v_pk_fma_f32 v[48:49], v[26:27], v[18:19], v[48:49]
	v_mul_f32_e32 v52, 0xbfb8aa3b, v46
	v_mul_f32_e32 v50, 0xbfb8aa3b, v48
	v_mul_f32_e32 v51, 0xbfb8aa3b, v49
	v_mul_f32_e32 v53, 0xbfb8aa3b, v47
	v_exp_f32_e32 v50, v50
	v_exp_f32_e32 v51, v51
	v_exp_f32_e32 v52, v52
	v_exp_f32_e32 v53, v53
	v_add_f32_e32 v50, 1.0, v50
	v_add_f32_e32 v51, 1.0, v51
	v_add_f32_e32 v52, 1.0, v52
	v_add_f32_e32 v53, 1.0, v53
	v_rcp_f32_e32 v50, v50
	v_rcp_f32_e32 v51, v51
	v_rcp_f32_e32 v52, v52
	v_rcp_f32_e32 v53, v53
	v_pk_fma_f32 v[32:33], v[32:33], v[16:17], v[12:13]
	v_pk_fma_f32 v[30:31], v[30:31], v[14:15], v[10:11]
	v_pk_fma_f32 v[32:33], v[28:29], v[24:25], v[32:33]
	v_pk_fma_f32 v[30:31], v[26:27], v[22:23], v[30:31]
	v_pk_mul_f32 v[46:47], v[46:47], v[52:53]
	v_pk_mul_f32 v[48:49], v[48:49], v[50:51]
	v_pk_fma_f32 v[32:33], v[94:95], v[20:21], v[32:33]
	v_pk_fma_f32 v[30:31], v[96:97], v[18:19], v[30:31]
	v_pk_mul_f32 v[36:37], v[36:37], v[46:47]
	v_pk_mul_f32 v[34:35], v[34:35], v[48:49]
	v_mul_f32_e32 v46, 0xbfb8aa3b, v30
	v_mul_f32_e32 v47, 0xbfb8aa3b, v31
	v_mul_f32_e32 v48, 0xbfb8aa3b, v32
	v_mul_f32_e32 v49, 0xbfb8aa3b, v33
	v_exp_f32_e32 v46, v46
	v_exp_f32_e32 v47, v47
	v_exp_f32_e32 v48, v48
	v_exp_f32_e32 v49, v49
	v_add_f32_e32 v46, 1.0, v46
	v_add_f32_e32 v47, 1.0, v47
	v_add_f32_e32 v48, 1.0, v48
	v_add_f32_e32 v49, 1.0, v49
	v_rcp_f32_e32 v46, v46
	v_rcp_f32_e32 v47, v47
	v_rcp_f32_e32 v48, v48
	v_rcp_f32_e32 v49, v49
	v_pk_fma_f32 v[28:29], v[28:29], v[16:17], v[12:13]
	v_pk_fma_f32 v[26:27], v[26:27], v[14:15], v[10:11]
	v_pk_fma_f32 v[28:29], v[94:95], v[24:25], v[28:29]
	v_pk_fma_f32 v[26:27], v[96:97], v[22:23], v[26:27]
	v_pk_mul_f32 v[32:33], v[32:33], v[48:49]
	v_pk_mul_f32 v[46:47], v[30:31], v[46:47]
	v_pk_fma_f32 v[28:29], v[86:87], v[20:21], v[28:29]
	v_pk_fma_f32 v[26:27], v[88:89], v[18:19], v[26:27]
	v_pk_mul_f32 v[30:31], v[106:107], v[32:33]
	v_pk_mul_f32 v[32:33], v[108:109], v[46:47]
	v_mul_f32_e32 v46, 0xbfb8aa3b, v26
	v_mul_f32_e32 v47, 0xbfb8aa3b, v27
	v_mul_f32_e32 v48, 0xbfb8aa3b, v28
	v_mul_f32_e32 v49, 0xbfb8aa3b, v29
	v_exp_f32_e32 v46, v46
	v_exp_f32_e32 v47, v47
	v_exp_f32_e32 v48, v48
	v_exp_f32_e32 v49, v49
; __device__ __forceinline__ u32x4 pack8(const f32x4 a, const f32x4 b) { u32x4 w; w.x = cvt_pk_bf16(a.x, a.y); w.y = cvt_pk_bf16(a.z, a.w); w.z = cvt_pk_bf16(b.x, b.y); w.w = cvt_pk_bf16(b.z, b.w); return w; }
; __device__ __forceinline__ f32x4 silu4(const f32x4 p) { f32x4 r; r.x = siluf(p.x); r.y = siluf(p.y); r.z = siluf(p.z); r.w = siluf(p.w); return r; }
;     __device__ __forceinline__ void operator()(f32x4 (&acc)[2][2][4][2], const pg8::Unit& u, int ui, int wr, int wc, int fr, int fq) const {
;     ...
; #pragma unroll
;             for (int j = 0; j < 8; ++j) { const f32x4 x = acc[j >> 2][0][j & 3][n];
;                 const f32x4 cv = cbv + w0 * p2 + w1 * p1 + w2 * x;
;                 acc[j >> 2][1][j & 3][n] = silu4(cv) * acc[j >> 2][1][j & 3][n];
;                 p2 = p1; p1 = x; }
;         }
; #pragma unroll
;         for (int j = 0; j < 8; ++j) *(u32x4*)(ACT + (size_t)u.pm * (256 * DFF) + (size_t)(jc >> 6) * (256 * 64) + (lrow + j) * 64 + (jc & 63)) = pack8(acc[j >> 2][1][j & 3][0], acc[j >> 2][1][j & 3][1]);
	v_add_f32_e32 v46, 1.0, v46
	v_add_f32_e32 v47, 1.0, v47
	v_add_f32_e32 v48, 1.0, v48
	v_add_f32_e32 v49, 1.0, v49
	v_rcp_f32_e32 v46, v46
	v_rcp_f32_e32 v47, v47
	v_rcp_f32_e32 v48, v48
	v_rcp_f32_e32 v49, v49
	v_mul_f32_e32 v137, 0xbfb8aa3b, v131
	v_pk_mul_f32 v[46:47], v[26:27], v[46:47]
	v_exp_f32_e32 v134, v134
	v_pk_mul_f32 v[28:29], v[28:29], v[48:49]
	v_pk_fma_f32 v[48:49], v[94:95], v[16:17], v[12:13]
	v_pk_mul_f32 v[26:27], v[98:99], v[28:29]
	v_pk_mul_f32 v[28:29], v[100:101], v[46:47]
	v_pk_fma_f32 v[46:47], v[96:97], v[14:15], v[10:11]
	v_pk_fma_f32 v[48:49], v[86:87], v[24:25], v[48:49]
	v_pk_fma_f32 v[46:47], v[88:89], v[22:23], v[46:47]
	v_pk_fma_f32 v[48:49], v[80:81], v[20:21], v[48:49]
	v_pk_fma_f32 v[46:47], v[78:79], v[18:19], v[46:47]
	v_mul_f32_e32 v52, 0xbfb8aa3b, v48
	v_mul_f32_e32 v50, 0xbfb8aa3b, v46
	v_mul_f32_e32 v51, 0xbfb8aa3b, v47
	v_mul_f32_e32 v53, 0xbfb8aa3b, v49
	v_exp_f32_e32 v50, v50
	v_exp_f32_e32 v51, v51
	v_exp_f32_e32 v52, v52
	v_exp_f32_e32 v53, v53
	v_add_f32_e32 v50, 1.0, v50
	v_add_f32_e32 v51, 1.0, v51
	v_add_f32_e32 v52, 1.0, v52
	v_add_f32_e32 v53, 1.0, v53
	v_rcp_f32_e32 v50, v50
	v_rcp_f32_e32 v51, v51
	v_rcp_f32_e32 v52, v52
	v_rcp_f32_e32 v53, v53
	v_exp_f32_e32 v135, v135
	v_pk_mul_f32 v[50:51], v[46:47], v[50:51]
	v_exp_f32_e32 v136, v136
	v_pk_mul_f32 v[48:49], v[48:49], v[52:53]
	v_pk_fma_f32 v[52:53], v[88:89], v[14:15], v[10:11]
	v_pk_mul_f32 v[46:47], v[92:93], v[48:49]
	v_pk_mul_f32 v[48:49], v[90:91], v[50:51]
	v_pk_fma_f32 v[50:51], v[86:87], v[16:17], v[12:13]
	v_pk_fma_f32 v[52:53], v[78:79], v[22:23], v[52:53]
	v_pk_fma_f32 v[50:51], v[80:81], v[24:25], v[50:51]
	v_pk_fma_f32 v[52:53], v[70:71], v[18:19], v[52:53]
	v_pk_fma_f32 v[50:51], v[72:73], v[20:21], v[50:51]
	v_mul_f32_e32 v54, 0xbfb8aa3b, v52
	v_mul_f32_e32 v56, 0xbfb8aa3b, v50
	v_mul_f32_e32 v57, 0xbfb8aa3b, v51
	v_mul_f32_e32 v55, 0xbfb8aa3b, v53
	v_exp_f32_e32 v56, v56
	v_exp_f32_e32 v57, v57
	v_exp_f32_e32 v54, v54
	v_exp_f32_e32 v55, v55
	v_add_f32_e32 v56, 1.0, v56
	v_add_f32_e32 v57, 1.0, v57
	v_add_f32_e32 v54, 1.0, v54
	v_add_f32_e32 v55, 1.0, v55
	v_rcp_f32_e32 v56, v56
	v_rcp_f32_e32 v57, v57
	v_rcp_f32_e32 v54, v54
	v_rcp_f32_e32 v55, v55
	v_exp_f32_e32 v137, v137
	v_pk_mul_f32 v[50:51], v[50:51], v[56:57]
	v_pk_fma_f32 v[56:57], v[78:79], v[14:15], v[10:11]
	v_pk_mul_f32 v[52:53], v[52:53], v[54:55]
	v_pk_fma_f32 v[54:55], v[80:81], v[16:17], v[12:13]
	v_pk_fma_f32 v[56:57], v[70:71], v[22:23], v[56:57]
	v_pk_fma_f32 v[10:11], v[70:71], v[14:15], v[10:11]
	v_pk_fma_f32 v[54:55], v[72:73], v[24:25], v[54:55]
	v_pk_fma_f32 v[56:57], v[6:7], v[18:19], v[56:57]
	v_pk_fma_f32 v[12:13], v[72:73], v[16:17], v[12:13]
	v_pk_fma_f32 v[6:7], v[6:7], v[22:23], v[10:11]
	v_pk_fma_f32 v[54:55], v[8:9], v[20:21], v[54:55]
	v_pk_fma_f32 v[8:9], v[8:9], v[24:25], v[12:13]
	v_pk_fma_f32 v[2:3], v[2:3], v[18:19], v[6:7]
	v_pk_fma_f32 v[4:5], v[4:5], v[20:21], v[8:9]
	v_mul_f32_e32 v6, 0xbfb8aa3b, v2
	v_mul_f32_e32 v7, 0xbfb8aa3b, v3
	v_exp_f32_e32 v6, v6
	v_exp_f32_e32 v7, v7
	v_mul_f32_e32 v8, 0xbfb8aa3b, v4
	v_mul_f32_e32 v9, 0xbfb8aa3b, v5
	v_exp_f32_e32 v8, v8
	v_exp_f32_e32 v9, v9
	v_add_f32_e32 v6, 1.0, v6
	v_add_f32_e32 v7, 1.0, v7
	v_rcp_f32_e32 v6, v6
	v_rcp_f32_e32 v7, v7
	v_add_f32_e32 v8, 1.0, v8
	v_add_f32_e32 v9, 1.0, v9
	v_rcp_f32_e32 v8, v8
	v_rcp_f32_e32 v9, v9
	v_pk_mul_f32 v[2:3], v[2:3], v[6:7]
	v_mul_f32_e32 v58, 0xbfb8aa3b, v56
	v_mul_f32_e32 v59, 0xbfb8aa3b, v57
	v_mul_f32_e32 v60, 0xbfb8aa3b, v54
	v_mul_f32_e32 v61, 0xbfb8aa3b, v55
	v_pk_mul_f32 v[4:5], v[4:5], v[8:9]
	v_pk_mul_f32 v[8:9], v[68:69], v[2:3]
	v_ashrrev_i32_e32 v2, 6, v170
	v_exp_f32_e32 v58, v58
	v_exp_f32_e32 v59, v59
	v_exp_f32_e32 v60, v60
	v_exp_f32_e32 v61, v61
	v_ashrrev_i32_e32 v3, 31, v2
	v_lshlrev_b64 v[10:11], 15, v[2:3]
	v_and_b32_e32 v12, 0x80, v0
	v_lshlrev_b32_e32 v12, 6, v12
	v_and_b32_e32 v248, 0x78, v0
	v_lshl_or_b32 v12, v248, 2, v12
	v_and_b32_e32 v14, 56, v170
	v_lshl_add_u64 v[10:11], s[10:11], 0, v[10:11]
	v_ashrrev_i32_e32 v13, 31, v12
	v_lshl_add_u64 v[10:11], v[12:13], 1, v[10:11]
	v_and_b32_e32 v248, 32, v14
	v_lshlrev_b32_e32 v248, 5, v248
	v_and_b32_e32 v0, 24, v14
	v_lshl_or_b32 v0, v0, 1, v248
	v_mov_b32_e32 v250, 0x1000
	v_mov_b32_e32 v251, 0
	v_add_f32_e32 v134, 1.0, v134
	v_add_f32_e32 v135, 1.0, v135
	v_add_f32_e32 v136, 1.0, v136
	v_add_f32_e32 v137, 1.0, v137
	v_add_f32_e32 v58, 1.0, v58
	v_add_f32_e32 v59, 1.0, v59
	v_add_f32_e32 v60, 1.0, v60
	v_add_f32_e32 v61, 1.0, v61
	v_pk_mul_f32 v[6:7], v[66:67], v[4:5]
	v_cvt_pk_bf16_f32 v2, v104, v105
	v_cvt_pk_bf16_f32 v3, v102, v103
	v_cvt_pk_bf16_f32 v4, v44, v45
	v_cvt_pk_bf16_f32 v5, v42, v43
	v_lshl_add_u64 v[10:11], v[10:11], 0, v[0:1]
	v_rcp_f32_e32 v134, v134
	v_rcp_f32_e32 v135, v135
	v_rcp_f32_e32 v136, v136
	v_rcp_f32_e32 v137, v137
	v_rcp_f32_e32 v58, v58
	v_rcp_f32_e32 v59, v59
	v_rcp_f32_e32 v60, v60
	v_rcp_f32_e32 v61, v61
	global_store_dwordx4 v[10:11], v[2:5], off
	v_pk_mul_f32 v[126:127], v[174:175], v[126:127]
	v_pk_mul_f32 v[128:129], v[172:173], v[128:129]
	v_cvt_pk_bf16_f32 v2, v112, v113
	v_cvt_pk_bf16_f32 v3, v110, v111
	v_cvt_pk_bf16_f32 v4, v34, v35
	v_cvt_pk_bf16_f32 v5, v36, v37
	global_store_dwordx4 v[10:11], v[2:5], off offset:2048
	v_pk_mul_f32 v[130:131], v[130:131], v[136:137]
	v_pk_mul_f32 v[132:133], v[132:133], v[134:135]
	v_cvt_pk_bf16_f32 v2, v116, v117
	v_cvt_pk_bf16_f32 v3, v114, v115
	v_cvt_pk_bf16_f32 v4, v32, v33
	v_cvt_pk_bf16_f32 v5, v30, v31
	v_lshl_add_u64 v[10:11], v[10:11], 0, v[250:251]
	global_store_dwordx4 v[10:11], v[2:5], off
	v_pk_mul_f32 v[50:51], v[84:85], v[50:51]
	v_pk_mul_f32 v[52:53], v[82:83], v[52:53]
	v_cvt_pk_bf16_f32 v2, v120, v121
	v_cvt_pk_bf16_f32 v3, v118, v119
	v_cvt_pk_bf16_f32 v4, v28, v29
	v_cvt_pk_bf16_f32 v5, v26, v27
	global_store_dwordx4 v[10:11], v[2:5], off offset:2048
	v_pk_mul_f32 v[54:55], v[54:55], v[60:61]
	v_pk_mul_f32 v[56:57], v[56:57], v[58:59]
	v_cvt_pk_bf16_f32 v2, v124, v125
	v_cvt_pk_bf16_f32 v3, v122, v123
	v_cvt_pk_bf16_f32 v4, v48, v49
	v_cvt_pk_bf16_f32 v5, v46, v47
	v_lshl_add_u64 v[10:11], v[10:11], 0, v[250:251]
	global_store_dwordx4 v[10:11], v[2:5], off
	v_pk_mul_f32 v[130:131], v[142:143], v[130:131]
	v_pk_mul_f32 v[132:133], v[144:145], v[132:133]
	v_cvt_pk_bf16_f32 v2, v128, v129
	v_cvt_pk_bf16_f32 v3, v126, v127
	v_cvt_pk_bf16_f32 v4, v52, v53
	v_cvt_pk_bf16_f32 v5, v50, v51
	v_pk_mul_f32 v[54:55], v[74:75], v[54:55]
	v_pk_mul_f32 v[56:57], v[76:77], v[56:57]
	global_store_dwordx4 v[10:11], v[2:5], off offset:2048
	s_mov_b64 s[10:11], -1
	s_nop 0
	v_cvt_pk_bf16_f32 v2, v132, v133
	v_cvt_pk_bf16_f32 v3, v130, v131
	v_cvt_pk_bf16_f32 v4, v56, v57
	v_cvt_pk_bf16_f32 v5, v54, v55
	v_lshl_add_u64 v[10:11], v[10:11], 0, v[250:251]
	global_store_dwordx4 v[10:11], v[2:5], off
	s_nop 1
	v_cvt_pk_bf16_f32 v2, v40, v41
	v_cvt_pk_bf16_f32 v3, v38, v39
	v_cvt_pk_bf16_f32 v4, v8, v9
	v_cvt_pk_bf16_f32 v5, v6, v7
	global_store_dwordx4 v[10:11], v[2:5], off offset:2048
	s_cbranch_vccnz .LBB0_1252
	s_branch .LBB0_1251

;     __host__ __device__ __forceinline__ bool next(int i, Unit& u) const { const int vv = vid + (i / 5) * G; if (vv >= 256) return false; u.pm = vv >> 2; u.pn = (vv & 3) + 4 * (i % 5); return true; }
;     __host__ __device__ __forceinline__ bool next(int i, pg8::Unit& u) const { const long Lx = (long)i * G + c; if (Lx >= 128) return false; const int Lq = (int)Lx; u.pm = 8 * (Lq >> 5) + (Lq & 7); u.pn = (Lq >> 3) & 3; return true; }
;     __device__ __forceinline__ size_t b_off(const pg8::Unit& u) const { return (size_t)(u.pm >> 3) * 4 * 131072; }
;     ...
;     for (;;) {
;         const bool has_next = S.next(ui + 1, nxt);
;         const char* nA = has_next ? (const char*)g.A + (size_t)nxt.pm * tstepA + (size_t)nxt.pn * APN + kofA : cA; const char* nB = has_next ? (const char*)g.Bt + (size_t)nxt.pn * tstepB + S.b_off(nxt) + kofB : cB;
.LBB0_1432:
	s_andn2_b64 vcc, exec, s[6:7]
	s_mov_b32 s86, s83
	s_mov_b32 s87, s85
	s_mov_b64 s[10:11], s[26:27]
	s_mov_b64 s[28:29], s[24:25]
	s_cbranch_vccz .LBB0_1518
	s_branch .Ldn_setup2

;     ...
;         for (int t = 0; t < nt; t += 2) {
;             const bool last = (t == nt - 2);
;             const char* a1 = cA + (ptrdiff_t)(t + 1) * kstepA;
;             const char* a2 = last ? nA : cA + (ptrdiff_t)(t + 2) * kstepA; const char* b2 = last ? nB : cB + (ptrdiff_t)(t + 2) * kstep;
;             const char* a3 = a2 + kstepA; const char* b3 = b2 + kstep;
.Ldn_s_1443:
	s_mov_b32 s56, 0
	s_cmpk_lg_i32 s56, 0x56
	s_cselect_b64 s[8:9], -1, 0
	s_cmpk_eq_i32 s56, 0x56
	s_mov_b64 s[30:31], s[24:25]
	s_cbranch_scc1 .Ldn_s_1447
	s_add_i32 s44, s56, 2
	s_lshl_b64 s[30:31], s[44:45], 15
	s_sub_u32 s30, 0, s30
	s_subb_u32 s31, 0, s31
	s_add_u32 s30, s28, s30
	s_addc_u32 s31, s29, s31

; #define PG8_STAGE(bufoff, gbase, voff) do { _Pragma("unroll") for (int _i = 0; _i < 2; ++_i) \
;         __builtin_amdgcn_global_load_lds((const unsigned*)((const char*)(gbase) + (voff)[_i]), (PG8_LAS unsigned*)(lds + (bufoff) + ldsw + _i * 8192), 16, 0, 0); } while (0)
; #define PG8_LDA(dst, b, h) do { _Pragma("unroll") for (int m = 0; m < 4; ++m) _Pragma("unroll") for (int k = 0; k < 2; ++k) dst[m][k] = *(const PG8_LAS bf16x8*)(lds + PG8_SA(b, h) + aoff + m * 2048 + k * 1024); } while (0)
; #define PG8_LDB(dst, b, h) do { _Pragma("unroll") for (int n = 0; n < 2; ++n) _Pragma("unroll") for (int k = 0; k < 2; ++k) dst[n][k] = *(const PG8_LAS bf16x8*)(lds + PG8_SB(b, h) + boff + n * 2048 + k * 1024); } while (0)
; #define PG8_MMA(ai, bj, At, Bt) do { __builtin_amdgcn_s_setprio(1); _Pragma("unroll") for (int m = 0; m < 4; ++m) _Pragma("unroll") for (int n = 0; n < 2; ++n) _Pragma("unroll") for (int k = 0; k < 2; ++k) \
;         acc[ai][bj][m][n] = __builtin_amdgcn_mfma_f32_16x16x32_bf16(Bt[n][k], At[m][k], acc[ai][bj][m][n], 0, 0, 0); __builtin_amdgcn_s_setprio(0); } while (0)
; #define PG8_WAIT_V(n) asm volatile("s_waitcnt vmcnt(" #n ")" ::: "memory")
; #define PG8_WAIT_L(n) asm volatile("s_waitcnt lgkmcnt(" #n ")" ::: "memory")
; #define PG8_BAR __builtin_amdgcn_s_barrier()
; #define PG8_SCHED __builtin_amdgcn_sched_barrier(0)
;     ...
;             if (last && has_next) S.a_ready(nxt);
;             if constexpr (SP2) {
;             PG8_LDB(B0, 0, 0); PG8_LDB(B1, 0, 1); PG8_SCHED; PG8_LDA(At, 0, 0); PG8_STAGE(PG8_SA(1, 1), a1 + hstepA, voffA);
;             PG8_WAIT_V(8); PG8_WAIT_L(0); PG8_BAR; PG8_MMA(0, 0, At, B0); PG8_MMA(0, 1, At, B1); PG8_BAR; PG8_SCHED;
;             PG8_LDA(At, 0, 1); PG8_STAGE(PG8_SB(0, 0), b2, voffB); PG8_STAGE(PG8_SB(0, 1), b2 + hstepB, voffB); PG8_STAGE(PG8_SA(0, 0), a2, voffA);
;             PG8_WAIT_V(8); PG8_WAIT_L(0); PG8_BAR; PG8_MMA(1, 0, At, B0); PG8_MMA(1, 1, At, B1); PG8_BAR; PG8_SCHED;
.Ldn_s_1444:
	s_cmp_eq_u64 s[12:13], 0
	s_cbranch_scc1 .Ldn_nostg
	s_barrier
.Ldn_nostg:
	s_or_b32 s44, s56, 1
	s_lshl_b64 s[34:35], s[44:45], 15
	s_sub_u32 s34, 0, s34
	s_subb_u32 s35, 0, s35
	s_add_u32 s44, s28, s34
	s_addc_u32 s65, s29, s35
	s_add_u32 s34, s30, 0xffff8000
	s_addc_u32 s35, s31, -1
	s_add_i32 s66, 0, 0x10000
	v_add_u32_e32 v0, s66, v230
	s_add_i32 s90, 0, 0x14000
	s_waitcnt lgkmcnt(0)
	ds_read_b128 v[130:133], v0
	ds_read_b128 v[134:137], v0 offset:1024
	ds_read_b128 v[138:141], v0 offset:2048
	ds_read_b128 v[142:145], v0 offset:3072
	v_add_u32_e32 v0, s90, v230
	ds_read_b128 v[146:149], v0
	ds_read_b128 v[150:153], v0 offset:1024
	ds_read_b128 v[154:157], v0 offset:2048
	ds_read_b128 v[158:161], v0 offset:3072
	s_add_u32 s88, s44, 0x4000
	s_addc_u32 s89, s65, 0
	s_add_i32 m0, s46, 0xc000
	ds_read_b128 v[162:165], v231
	ds_read_b128 v[166:169], v231 offset:1024
	ds_read_b128 v[170:173], v231 offset:2048
	ds_read_b128 v[174:177], v231 offset:3072
	ds_read_b128 v[178:181], v231 offset:4096
	ds_read_b128 v[182:185], v231 offset:5120
	ds_read_b128 v[186:189], v231 offset:6144
	ds_read_b128 v[190:193], v231 offset:7168
	global_load_lds_dwordx4 v194, s[88:89]
	s_add_i32 m0, s46, 0xe000
	s_nop 0
	global_load_lds_dwordx4 v198, s[88:89]
	s_waitcnt vmcnt(8)
	s_waitcnt lgkmcnt(0)
	s_barrier
	s_setprio 1
	s_waitcnt lgkmcnt(0)
	v_mfma_f32_16x16x32_bf16 v[126:129], v[130:133], v[162:165], 0
	v_mfma_f32_16x16x32_bf16 v[126:129], v[134:137], v[166:169], v[126:129]
	v_mfma_f32_16x16x32_bf16 v[122:125], v[142:145], v[166:169], 0
	v_mfma_f32_16x16x32_bf16 v[122:125], v[138:141], v[162:165], v[122:125]
	v_mfma_f32_16x16x32_bf16 v[106:109], v[138:141], v[170:173], 0
	v_mfma_f32_16x16x32_bf16 v[106:109], v[142:145], v[174:177], v[106:109]
	v_mfma_f32_16x16x32_bf16 v[110:113], v[134:137], v[174:177], 0
	v_mfma_f32_16x16x32_bf16 v[110:113], v[130:133], v[170:173], v[110:113]
	v_mfma_f32_16x16x32_bf16 v[94:97], v[130:133], v[178:181], 0
	v_mfma_f32_16x16x32_bf16 v[94:97], v[134:137], v[182:185], v[94:97]
	v_mfma_f32_16x16x32_bf16 v[90:93], v[142:145], v[182:185], 0
	v_mfma_f32_16x16x32_bf16 v[90:93], v[138:141], v[178:181], v[90:93]
	v_mfma_f32_16x16x32_bf16 v[74:77], v[138:141], v[186:189], 0
	v_mfma_f32_16x16x32_bf16 v[74:77], v[142:145], v[190:193], v[74:77]
	v_mfma_f32_16x16x32_bf16 v[78:81], v[134:137], v[190:193], 0
	v_mfma_f32_16x16x32_bf16 v[78:81], v[130:133], v[186:189], v[78:81]
	s_setprio 0
	s_setprio 1
	v_mfma_f32_16x16x32_bf16 v[118:121], v[146:149], v[162:165], 0
	v_mfma_f32_16x16x32_bf16 v[118:121], v[150:153], v[166:169], v[118:121]
	v_mfma_f32_16x16x32_bf16 v[114:117], v[158:161], v[166:169], 0
	v_mfma_f32_16x16x32_bf16 v[114:117], v[154:157], v[162:165], v[114:117]
	v_mfma_f32_16x16x32_bf16 v[98:101], v[154:157], v[170:173], 0
	v_mfma_f32_16x16x32_bf16 v[98:101], v[158:161], v[174:177], v[98:101]
	v_mfma_f32_16x16x32_bf16 v[102:105], v[150:153], v[174:177], 0
	v_mfma_f32_16x16x32_bf16 v[102:105], v[146:149], v[170:173], v[102:105]
	v_mfma_f32_16x16x32_bf16 v[86:89], v[146:149], v[178:181], 0
	v_mfma_f32_16x16x32_bf16 v[86:89], v[150:153], v[182:185], v[86:89]
	v_mfma_f32_16x16x32_bf16 v[82:85], v[158:161], v[182:185], 0
	v_mfma_f32_16x16x32_bf16 v[82:85], v[154:157], v[178:181], v[82:85]
	v_mfma_f32_16x16x32_bf16 v[66:69], v[154:157], v[186:189], 0
	v_mfma_f32_16x16x32_bf16 v[66:69], v[158:161], v[190:193], v[66:69]
	v_mfma_f32_16x16x32_bf16 v[70:73], v[150:153], v[190:193], 0
	v_mfma_f32_16x16x32_bf16 v[70:73], v[146:149], v[186:189], v[70:73]
	s_setprio 0
	s_barrier
	s_add_i32 s44, s66, s41
	s_mov_b32 m0, s44
	ds_read_b128 v[162:165], v231 offset:16384
	ds_read_b128 v[166:169], v231 offset:17408
	ds_read_b128 v[170:173], v231 offset:18432
	ds_read_b128 v[174:177], v231 offset:19456
	ds_read_b128 v[178:181], v231 offset:20480
	ds_read_b128 v[182:185], v231 offset:21504
	ds_read_b128 v[186:189], v231 offset:22528
	ds_read_b128 v[190:193], v231 offset:23552
	global_load_lds_dwordx4 v196, s[8:9]
	s_add_i32 m0, s44, 0x2000
	s_add_u32 s88, s8, 0x4000
	s_addc_u32 s89, s9, 0
	s_add_i32 s44, s90, s41
	global_load_lds_dwordx4 v200, s[8:9]
	s_mov_b32 m0, s44
	s_nop 0
	global_load_lds_dwordx4 v196, s[88:89]
	s_add_i32 m0, s44, 0x2000
	s_nop 0
	global_load_lds_dwordx4 v200, s[88:89]
	s_mov_b32 m0, s46
	s_nop 0
	global_load_lds_dwordx4 v194, s[30:31]
	s_mov_b32 m0, s47
	s_nop 0
	global_load_lds_dwordx4 v198, s[30:31]
	s_waitcnt vmcnt(8)
	s_waitcnt lgkmcnt(0)
	s_barrier
	s_setprio 1
	s_waitcnt lgkmcnt(0)
	v_mfma_f32_16x16x32_bf16 v[62:65], v[130:133], v[162:165], 0
	v_mfma_f32_16x16x32_bf16 v[62:65], v[134:137], v[166:169], v[62:65]
	v_mfma_f32_16x16x32_bf16 v[58:61], v[142:145], v[166:169], 0
	v_mfma_f32_16x16x32_bf16 v[58:61], v[138:141], v[162:165], v[58:61]
	v_mfma_f32_16x16x32_bf16 v[42:45], v[138:141], v[170:173], 0
	v_mfma_f32_16x16x32_bf16 v[42:45], v[142:145], v[174:177], v[42:45]
	v_mfma_f32_16x16x32_bf16 v[46:49], v[134:137], v[174:177], 0
	v_mfma_f32_16x16x32_bf16 v[46:49], v[130:133], v[170:173], v[46:49]
	v_mfma_f32_16x16x32_bf16 v[30:33], v[130:133], v[178:181], 0
	v_mfma_f32_16x16x32_bf16 v[30:33], v[134:137], v[182:185], v[30:33]
	v_mfma_f32_16x16x32_bf16 v[26:29], v[142:145], v[182:185], 0
	v_mfma_f32_16x16x32_bf16 v[26:29], v[138:141], v[178:181], v[26:29]
	v_mfma_f32_16x16x32_bf16 v[10:13], v[138:141], v[186:189], 0
	v_mfma_f32_16x16x32_bf16 v[10:13], v[142:145], v[190:193], v[10:13]
	v_mfma_f32_16x16x32_bf16 v[14:17], v[134:137], v[190:193], 0
	v_mfma_f32_16x16x32_bf16 v[14:17], v[130:133], v[186:189], v[14:17]
	s_setprio 0
	s_setprio 1
	v_mfma_f32_16x16x32_bf16 v[54:57], v[146:149], v[162:165], 0
	v_mfma_f32_16x16x32_bf16 v[54:57], v[150:153], v[166:169], v[54:57]
	v_mfma_f32_16x16x32_bf16 v[50:53], v[158:161], v[166:169], 0
	v_mfma_f32_16x16x32_bf16 v[50:53], v[154:157], v[162:165], v[50:53]
	v_mfma_f32_16x16x32_bf16 v[34:37], v[154:157], v[170:173], 0
	v_mfma_f32_16x16x32_bf16 v[34:37], v[158:161], v[174:177], v[34:37]
	v_mfma_f32_16x16x32_bf16 v[38:41], v[150:153], v[174:177], 0
	v_mfma_f32_16x16x32_bf16 v[38:41], v[146:149], v[170:173], v[38:41]
	v_mfma_f32_16x16x32_bf16 v[22:25], v[146:149], v[178:181], 0
	v_mfma_f32_16x16x32_bf16 v[22:25], v[150:153], v[182:185], v[22:25]
	v_mfma_f32_16x16x32_bf16 v[18:21], v[158:161], v[182:185], 0
	v_mfma_f32_16x16x32_bf16 v[18:21], v[154:157], v[178:181], v[18:21]
	v_mfma_f32_16x16x32_bf16 v[2:5], v[154:157], v[186:189], 0
	v_mfma_f32_16x16x32_bf16 v[2:5], v[158:161], v[190:193], v[2:5]
	v_mfma_f32_16x16x32_bf16 v[6:9], v[150:153], v[190:193], 0
	v_mfma_f32_16x16x32_bf16 v[6:9], v[146:149], v[186:189], v[6:9]
	s_setprio 0
	s_barrier
	s_branch .Ldn_mid

; #define PG8_STAGE(bufoff, gbase, voff) do { _Pragma("unroll") for (int _i = 0; _i < 2; ++_i) \
;         __builtin_amdgcn_global_load_lds((const unsigned*)((const char*)(gbase) + (voff)[_i]), (PG8_LAS unsigned*)(lds + (bufoff) + ldsw + _i * 8192), 16, 0, 0); } while (0)
; #define PG8_LDA(dst, b, h) do { _Pragma("unroll") for (int m = 0; m < 4; ++m) _Pragma("unroll") for (int k = 0; k < 2; ++k) dst[m][k] = *(const PG8_LAS bf16x8*)(lds + PG8_SA(b, h) + aoff + m * 2048 + k * 1024); } while (0)
; #define PG8_LDB(dst, b, h) do { _Pragma("unroll") for (int n = 0; n < 2; ++n) _Pragma("unroll") for (int k = 0; k < 2; ++k) dst[n][k] = *(const PG8_LAS bf16x8*)(lds + PG8_SB(b, h) + boff + n * 2048 + k * 1024); } while (0)
; #define PG8_MMA(ai, bj, At, Bt) do { __builtin_amdgcn_s_setprio(1); _Pragma("unroll") for (int m = 0; m < 4; ++m) _Pragma("unroll") for (int n = 0; n < 2; ++n) _Pragma("unroll") for (int k = 0; k < 2; ++k) \
;         acc[ai][bj][m][n] = __builtin_amdgcn_mfma_f32_16x16x32_bf16(Bt[n][k], At[m][k], acc[ai][bj][m][n], 0, 0, 0); __builtin_amdgcn_s_setprio(0); } while (0)
; #define PG8_WAIT_V(n) asm volatile("s_waitcnt vmcnt(" #n ")" ::: "memory")
; #define PG8_WAIT_L(n) asm volatile("s_waitcnt lgkmcnt(" #n ")" ::: "memory")
; #define PG8_BAR __builtin_amdgcn_s_barrier()
; #define PG8_SCHED __builtin_amdgcn_sched_barrier(0)
;     ...
;             PG8_LDB(B0, 1, 0); PG8_LDB(B1, 1, 1); PG8_SCHED; PG8_LDA(At, 1, 0); PG8_STAGE(PG8_SA(0, 1), a2 + hstepA, voffA);
;             PG8_WAIT_V(8); PG8_WAIT_L(0); PG8_BAR; PG8_MMA(0, 0, At, B0); PG8_MMA(0, 1, At, B1); PG8_BAR; PG8_SCHED;
;             PG8_LDA(At, 1, 1); PG8_STAGE(PG8_SB(1, 0), b3, voffB); PG8_STAGE(PG8_SB(1, 1), b3 + hstepB, voffB); PG8_STAGE(PG8_SA(1, 0), a3, voffA);
;             PG8_WAIT_V(8); PG8_WAIT_L(0); PG8_BAR; PG8_MMA(1, 0, At, B0); PG8_MMA(1, 1, At, B1); PG8_BAR; PG8_SCHED;
.Ldn_mid:
	s_add_i32 s44, 0, 0x18000
	v_add_u32_e32 v0, s44, v230
	s_add_i32 s65, 0, 0x1c000
	ds_read_b128 v[130:133], v0
	ds_read_b128 v[134:137], v0 offset:1024
	ds_read_b128 v[138:141], v0 offset:2048
	ds_read_b128 v[142:145], v0 offset:3072
	v_add_u32_e32 v0, s65, v230
	ds_read_b128 v[146:149], v0
	ds_read_b128 v[150:153], v0 offset:1024
	ds_read_b128 v[154:157], v0 offset:2048
	ds_read_b128 v[158:161], v0 offset:3072
	s_add_u32 s30, s30, 0x4000
	s_addc_u32 s31, s31, 0
	s_mov_b32 m0, s48
	ds_read_b128 v[162:165], v231 offset:32768
	ds_read_b128 v[166:169], v231 offset:33792
	ds_read_b128 v[170:173], v231 offset:34816
	ds_read_b128 v[174:177], v231 offset:35840
	ds_read_b128 v[178:181], v231 offset:36864
	ds_read_b128 v[182:185], v231 offset:37888
	ds_read_b128 v[186:189], v231 offset:38912
	ds_read_b128 v[190:193], v231 offset:39936
	global_load_lds_dwordx4 v194, s[30:31]
	s_mov_b32 m0, s49
	s_nop 0
	global_load_lds_dwordx4 v198, s[30:31]
	s_waitcnt vmcnt(8)
	s_waitcnt lgkmcnt(0)
	s_barrier
	s_setprio 1
	s_waitcnt lgkmcnt(0)
	v_mfma_f32_16x16x32_bf16 v[126:129], v[130:133], v[162:165], v[126:129]
	v_mfma_f32_16x16x32_bf16 v[126:129], v[134:137], v[166:169], v[126:129]
	v_mfma_f32_16x16x32_bf16 v[122:125], v[142:145], v[166:169], v[122:125]
	v_mfma_f32_16x16x32_bf16 v[122:125], v[138:141], v[162:165], v[122:125]
	v_mfma_f32_16x16x32_bf16 v[106:109], v[138:141], v[170:173], v[106:109]
	v_mfma_f32_16x16x32_bf16 v[106:109], v[142:145], v[174:177], v[106:109]
	v_mfma_f32_16x16x32_bf16 v[110:113], v[134:137], v[174:177], v[110:113]
	v_mfma_f32_16x16x32_bf16 v[110:113], v[130:133], v[170:173], v[110:113]
	v_mfma_f32_16x16x32_bf16 v[94:97], v[130:133], v[178:181], v[94:97]
	v_mfma_f32_16x16x32_bf16 v[94:97], v[134:137], v[182:185], v[94:97]
	v_mfma_f32_16x16x32_bf16 v[90:93], v[142:145], v[182:185], v[90:93]
	v_mfma_f32_16x16x32_bf16 v[90:93], v[138:141], v[178:181], v[90:93]
	v_mfma_f32_16x16x32_bf16 v[74:77], v[138:141], v[186:189], v[74:77]
	v_mfma_f32_16x16x32_bf16 v[74:77], v[142:145], v[190:193], v[74:77]
	v_mfma_f32_16x16x32_bf16 v[78:81], v[134:137], v[190:193], v[78:81]
	v_mfma_f32_16x16x32_bf16 v[78:81], v[130:133], v[186:189], v[78:81]
	s_setprio 0
	s_setprio 1
	v_mfma_f32_16x16x32_bf16 v[118:121], v[146:149], v[162:165], v[118:121]
	v_mfma_f32_16x16x32_bf16 v[118:121], v[150:153], v[166:169], v[118:121]
	v_mfma_f32_16x16x32_bf16 v[114:117], v[158:161], v[166:169], v[114:117]
	v_mfma_f32_16x16x32_bf16 v[114:117], v[154:157], v[162:165], v[114:117]
	v_mfma_f32_16x16x32_bf16 v[98:101], v[154:157], v[170:173], v[98:101]
	v_mfma_f32_16x16x32_bf16 v[98:101], v[158:161], v[174:177], v[98:101]
	v_mfma_f32_16x16x32_bf16 v[102:105], v[150:153], v[174:177], v[102:105]
	v_mfma_f32_16x16x32_bf16 v[102:105], v[146:149], v[170:173], v[102:105]
	v_mfma_f32_16x16x32_bf16 v[86:89], v[146:149], v[178:181], v[86:89]
	v_mfma_f32_16x16x32_bf16 v[86:89], v[150:153], v[182:185], v[86:89]
	v_mfma_f32_16x16x32_bf16 v[82:85], v[158:161], v[182:185], v[82:85]
	v_mfma_f32_16x16x32_bf16 v[82:85], v[154:157], v[178:181], v[82:85]
	v_mfma_f32_16x16x32_bf16 v[66:69], v[154:157], v[186:189], v[66:69]
	v_mfma_f32_16x16x32_bf16 v[66:69], v[158:161], v[190:193], v[66:69]
	v_mfma_f32_16x16x32_bf16 v[70:73], v[150:153], v[190:193], v[70:73]
	v_mfma_f32_16x16x32_bf16 v[70:73], v[146:149], v[186:189], v[70:73]
	s_setprio 0
	s_barrier
	s_add_u32 s30, s8, 0xffff8000
	s_addc_u32 s31, s9, -1
	s_add_i32 s44, s44, s41
	s_mov_b32 m0, s44
	ds_read_b128 v[162:165], v231 offset:49152
	ds_read_b128 v[166:169], v231 offset:50176
	ds_read_b128 v[170:173], v231 offset:51200
	ds_read_b128 v[174:177], v231 offset:52224
	ds_read_b128 v[178:181], v231 offset:53248
	ds_read_b128 v[182:185], v231 offset:54272
	ds_read_b128 v[186:189], v231 offset:55296
	ds_read_b128 v[190:193], v231 offset:56320
	global_load_lds_dwordx4 v196, s[30:31]
	s_add_i32 m0, s44, 0x2000
	s_add_u32 s8, s8, 0xffffc000
	v_lshl_add_u64 v[202:203], s[30:31], 0, v[200:201]
	s_addc_u32 s9, s9, -1
	s_add_i32 s30, s65, s41
	global_load_lds_dwordx4 v[202:203], off
	s_mov_b32 m0, s30
	s_nop 0
	global_load_lds_dwordx4 v196, s[8:9]
	s_add_i32 m0, s30, 0x2000
	s_nop 0
	global_load_lds_dwordx4 v200, s[8:9]
	s_mov_b32 m0, s71
	s_nop 0
	global_load_lds_dwordx4 v194, s[34:35]
	v_lshl_add_u64 v[202:203], s[34:35], 0, v[198:199]
	s_mov_b32 m0, s80
	s_nop 0
	global_load_lds_dwordx4 v[202:203], off
	s_waitcnt vmcnt(8)
	s_waitcnt lgkmcnt(0)
	s_barrier
	s_setprio 1
	s_waitcnt lgkmcnt(0)
	v_mfma_f32_16x16x32_bf16 v[62:65], v[130:133], v[162:165], v[62:65]
	v_mfma_f32_16x16x32_bf16 v[62:65], v[134:137], v[166:169], v[62:65]
	v_mfma_f32_16x16x32_bf16 v[58:61], v[142:145], v[166:169], v[58:61]
	v_mfma_f32_16x16x32_bf16 v[58:61], v[138:141], v[162:165], v[58:61]
	v_mfma_f32_16x16x32_bf16 v[42:45], v[138:141], v[170:173], v[42:45]
	v_mfma_f32_16x16x32_bf16 v[42:45], v[142:145], v[174:177], v[42:45]
	v_mfma_f32_16x16x32_bf16 v[46:49], v[134:137], v[174:177], v[46:49]
	v_mfma_f32_16x16x32_bf16 v[46:49], v[130:133], v[170:173], v[46:49]
	v_mfma_f32_16x16x32_bf16 v[30:33], v[130:133], v[178:181], v[30:33]
	v_mfma_f32_16x16x32_bf16 v[30:33], v[134:137], v[182:185], v[30:33]
	v_mfma_f32_16x16x32_bf16 v[26:29], v[142:145], v[182:185], v[26:29]
	v_mfma_f32_16x16x32_bf16 v[26:29], v[138:141], v[178:181], v[26:29]
	v_mfma_f32_16x16x32_bf16 v[10:13], v[138:141], v[186:189], v[10:13]
	v_mfma_f32_16x16x32_bf16 v[10:13], v[142:145], v[190:193], v[10:13]
	v_mfma_f32_16x16x32_bf16 v[14:17], v[134:137], v[190:193], v[14:17]
	v_mfma_f32_16x16x32_bf16 v[14:17], v[130:133], v[186:189], v[14:17]
	s_setprio 0
	s_setprio 1
	v_mfma_f32_16x16x32_bf16 v[54:57], v[146:149], v[162:165], v[54:57]
	v_mfma_f32_16x16x32_bf16 v[54:57], v[150:153], v[166:169], v[54:57]
	v_mfma_f32_16x16x32_bf16 v[50:53], v[158:161], v[166:169], v[50:53]
	v_mfma_f32_16x16x32_bf16 v[50:53], v[154:157], v[162:165], v[50:53]
	v_mfma_f32_16x16x32_bf16 v[34:37], v[154:157], v[170:173], v[34:37]
	v_mfma_f32_16x16x32_bf16 v[34:37], v[158:161], v[174:177], v[34:37]
	v_mfma_f32_16x16x32_bf16 v[38:41], v[150:153], v[174:177], v[38:41]
	v_mfma_f32_16x16x32_bf16 v[38:41], v[146:149], v[170:173], v[38:41]
	v_mfma_f32_16x16x32_bf16 v[22:25], v[146:149], v[178:181], v[22:25]
	v_mfma_f32_16x16x32_bf16 v[22:25], v[150:153], v[182:185], v[22:25]
	v_mfma_f32_16x16x32_bf16 v[18:21], v[158:161], v[182:185], v[18:21]
	v_mfma_f32_16x16x32_bf16 v[18:21], v[154:157], v[178:181], v[18:21]
	v_mfma_f32_16x16x32_bf16 v[2:5], v[154:157], v[186:189], v[2:5]
	v_mfma_f32_16x16x32_bf16 v[2:5], v[158:161], v[190:193], v[2:5]
	v_mfma_f32_16x16x32_bf16 v[6:9], v[150:153], v[190:193], v[6:9]
	v_mfma_f32_16x16x32_bf16 v[6:9], v[146:149], v[186:189], v[6:9]
	s_setprio 0
	s_barrier
	s_cmpk_gt_u32 s56, 0x55
	s_mov_b32 s56, s57
	s_cbranch_scc1 .LBB0_1449

; #define PG8_BAR __builtin_amdgcn_s_barrier()
;     ...
;         if (!has_next) break;
; #pragma unroll
;         for (int a = 0; a < 2; ++a)
; #pragma unroll
;             for (int b = 0; b < 2; ++b)
; #pragma unroll
;                 for (int m = 0; m < 4; ++m)
; #pragma unroll
;                     for (int n = 0; n < 2; ++n) acc[a][b][m][n] = (f32x4){0.f, 0.f, 0.f, 0.f};
;         cur = nxt; cA = nA; cB = nB; ++ui;
;         if constexpr (ALIGN_EPI) { if (wr == 1) PG8_BAR; }
.LBB0_1515:
	s_or_b64 exec, exec, s[8:9]
	s_and_b64 vcc, exec, s[6:7]
	s_mov_b64 s[6:7], -1
	s_cbranch_vccnz .LBB0_1432
	s_branch .LBB0_1431
